# v37 + leading wave half (wr==0) holds priority 1 through the GEMM epilogue and tile hand-over
# baseline (speedup 1.0000x reference)
; #define PG8_STAGE(bufoff, gbase, voff) do { _Pragma("unroll") for (int _i = 0; _i < 2; ++_i) \
;         __builtin_amdgcn_global_load_lds((const unsigned*)((const char*)(gbase) + (voff)[_i]), (PG8_LAS unsigned*)(lds + (bufoff) + ldsw + _i * 8192), 16, 0, 0); } while (0)
; #define PG8_LDA(dst, b, h) do { _Pragma("unroll") for (int m = 0; m < 4; ++m) _Pragma("unroll") for (int k = 0; k < 2; ++k) dst[m][k] = *(const PG8_LAS bf16x8*)(lds + PG8_SA(b, h) + aoff + m * 2048 + k * 1024); } while (0)
; #define PG8_LDB(dst, b, h) do { _Pragma("unroll") for (int n = 0; n < 2; ++n) _Pragma("unroll") for (int k = 0; k < 2; ++k) dst[n][k] = *(const PG8_LAS bf16x8*)(lds + PG8_SB(b, h) + boff + n * 2048 + k * 1024); } while (0)
; #define PG8_WAIT_V(n) asm volatile("s_waitcnt vmcnt(" #n ")" ::: "memory")
; #define PG8_WAIT_L(n) asm volatile("s_waitcnt lgkmcnt(" #n ")" ::: "memory")
; #define PG8_BAR __builtin_amdgcn_s_barrier()
; #define PG8_SCHED __builtin_amdgcn_sched_barrier(0)
; template <class Epi, class Sched, bool ALIGN_EPI = false, bool SP2 = false, bool F16 = false>
; __device__ __forceinline__ void gemm_phase(PG8_LAS unsigned char* lds, const Gemm g, const Sched& S, const Epi& E) {
;     ...
;             if constexpr (SP2) {
;             PG8_LDB(B0, 0, 0); PG8_LDB(B1, 0, 1); PG8_SCHED; PG8_LDA(At, 0, 0); PG8_STAGE(PG8_SA(1, 1), a1 + hstepA, voffA);
;             PG8_WAIT_V(8); PG8_WAIT_L(0); PG8_BAR; PG8_MMA(0, 0, At, B0); PG8_MMA(0, 1, At, B1); PG8_BAR; PG8_SCHED;
;             PG8_LDA(At, 0, 1); PG8_STAGE(PG8_SB(0, 0), b2, voffB); PG8_STAGE(PG8_SB(0, 1), b2 + hstepB, voffB); PG8_STAGE(PG8_SA(0, 0), a2, voffA);
;             PG8_WAIT_V(8); PG8_WAIT_L(0); PG8_BAR; PG8_MMA(1, 0, At, B0); PG8_MMA(1, 1, At, B1); PG8_BAR; PG8_SCHED;
.Lpk_gu:
	s_setprio 0
	s_add_i32 s82, s54, 2
	s_add_u32 s83, s52, 0x80
	s_addc_u32 s55, s53, 0
	s_add_i32 vcc_lo, 0, 0x10000
	s_cmp_eq_u32 s74, s54
	s_cselect_b32 s55, s39, s55
	s_cselect_b32 s54, s38, s83
	s_cselect_b32 s95, s47, s81
	s_cselect_b32 s94, s46, s80
	s_add_i32 s83, 0, 0x14000
	ds_read_b128 v[130:133], v139
	ds_read_b128 v[134:137], v139 offset:1024
	ds_read_b128 v[152:155], v139 offset:2048
	ds_read_b128 v[156:159], v139 offset:3072
	ds_read_b128 v[160:163], v141
	ds_read_b128 v[166:169], v141 offset:1024
	ds_read_b128 v[184:187], v141 offset:2048
	ds_read_b128 v[188:191], v141 offset:3072
	s_add_i32 m0, s22, 0xc000
	ds_read_b128 v[192:195], v183
	ds_read_b128 v[204:207], v183 offset:1024
	ds_read_b128 v[208:211], v183 offset:2048
	ds_read_b128 v[212:215], v183 offset:3072
	ds_read_b128 v[216:219], v183 offset:4096
	ds_read_b128 v[220:223], v183 offset:5120
	ds_read_b128 v[224:227], v183 offset:6144
	ds_read_b128 v[228:231], v183 offset:7168
	global_load_lds_dwordx4 v148, s[52:53]
	s_add_i32 m0, s22, 0xe000
	s_nop 0
	global_load_lds_dwordx4 v150, s[52:53]
	s_waitcnt vmcnt(8)
	s_waitcnt lgkmcnt(0)
	s_setprio 1
	s_barrier
	v_mfma_f32_16x16x32_f16 v[122:125], v[130:133], v[192:195], 0
	v_mfma_f32_16x16x32_f16 v[114:117], v[152:155], v[192:195], 0
	v_mfma_f32_16x16x32_f16 v[106:109], v[130:133], v[208:211], 0
	v_mfma_f32_16x16x32_f16 v[98:101], v[152:155], v[208:211], 0
	v_mfma_f32_16x16x32_f16 v[90:93], v[130:133], v[216:219], 0
	v_mfma_f32_16x16x32_f16 v[82:85], v[152:155], v[216:219], 0
	v_mfma_f32_16x16x32_f16 v[74:77], v[130:133], v[224:227], 0
	v_mfma_f32_16x16x32_f16 v[66:69], v[152:155], v[224:227], 0
	v_mfma_f32_16x16x32_f16 v[122:125], v[134:137], v[204:207], v[122:125]
	v_mfma_f32_16x16x32_f16 v[114:117], v[156:159], v[204:207], v[114:117]
	v_mfma_f32_16x16x32_f16 v[106:109], v[134:137], v[212:215], v[106:109]
	v_mfma_f32_16x16x32_f16 v[98:101], v[156:159], v[212:215], v[98:101]
	v_mfma_f32_16x16x32_f16 v[90:93], v[134:137], v[220:223], v[90:93]
	v_mfma_f32_16x16x32_f16 v[82:85], v[156:159], v[220:223], v[82:85]
	v_mfma_f32_16x16x32_f16 v[74:77], v[134:137], v[228:231], v[74:77]
	v_mfma_f32_16x16x32_f16 v[66:69], v[156:159], v[228:231], v[66:69]
	v_mfma_f32_16x16x32_f16 v[126:129], v[160:163], v[192:195], 0
	v_mfma_f32_16x16x32_f16 v[118:121], v[184:187], v[192:195], 0
	v_mfma_f32_16x16x32_f16 v[110:113], v[160:163], v[208:211], 0
	v_mfma_f32_16x16x32_f16 v[102:105], v[184:187], v[208:211], 0
	v_mfma_f32_16x16x32_f16 v[94:97], v[160:163], v[216:219], 0
	v_mfma_f32_16x16x32_f16 v[86:89], v[184:187], v[216:219], 0
	v_mfma_f32_16x16x32_f16 v[78:81], v[160:163], v[224:227], 0
	v_mfma_f32_16x16x32_f16 v[70:73], v[184:187], v[224:227], 0
	v_mfma_f32_16x16x32_f16 v[126:129], v[166:169], v[204:207], v[126:129]
	v_mfma_f32_16x16x32_f16 v[118:121], v[188:191], v[204:207], v[118:121]
	v_mfma_f32_16x16x32_f16 v[110:113], v[166:169], v[212:215], v[110:113]
	v_mfma_f32_16x16x32_f16 v[102:105], v[188:191], v[212:215], v[102:105]
	v_mfma_f32_16x16x32_f16 v[94:97], v[166:169], v[220:223], v[94:97]
	v_mfma_f32_16x16x32_f16 v[86:89], v[188:191], v[220:223], v[86:89]
	v_mfma_f32_16x16x32_f16 v[78:81], v[166:169], v[228:231], v[78:81]
	v_mfma_f32_16x16x32_f16 v[70:73], v[188:191], v[228:231], v[70:73]
	s_barrier
	s_setprio 0
	s_add_i32 vcc_lo, vcc_lo, s2
	s_mov_b32 m0, vcc_lo
	s_nop 0
	global_load_lds_dwordx4 v142, s[94:95]
	ds_read_b128 v[192:195], v183 offset:16384
	ds_read_b128 v[204:207], v183 offset:17408
	ds_read_b128 v[208:211], v183 offset:18432
	ds_read_b128 v[212:215], v183 offset:19456
	ds_read_b128 v[216:219], v183 offset:20480
	ds_read_b128 v[220:223], v183 offset:21504
	ds_read_b128 v[224:227], v183 offset:22528
	ds_read_b128 v[228:231], v183 offset:23552
	s_add_i32 m0, vcc_lo, 0x2000
	s_nop 0
	global_load_lds_dwordx4 v138, s[94:95]
	s_add_i32 s83, s83, s2
	s_add_u32 s94, s94, s48
	s_addc_u32 s95, s95, 0
	s_mov_b32 m0, s83
	s_nop 0
	global_load_lds_dwordx4 v142, s[94:95]
	s_add_i32 m0, s83, 0x2000
	s_nop 0
	global_load_lds_dwordx4 v138, s[94:95]
	s_mov_b32 m0, s22
	s_nop 0
	global_load_lds_dwordx4 v144, s[54:55]
	s_mov_b32 m0, s33
	s_nop 0
	global_load_lds_dwordx4 v140, s[54:55]
	s_waitcnt vmcnt(8)
	s_waitcnt lgkmcnt(0)
	s_setprio 1
	s_barrier
	v_mfma_f32_16x16x32_f16 v[58:61], v[130:133], v[192:195], 0
	v_mfma_f32_16x16x32_f16 v[50:53], v[152:155], v[192:195], 0
	v_mfma_f32_16x16x32_f16 v[42:45], v[130:133], v[208:211], 0
	v_mfma_f32_16x16x32_f16 v[34:37], v[152:155], v[208:211], 0
	v_mfma_f32_16x16x32_f16 v[26:29], v[130:133], v[216:219], 0
	v_mfma_f32_16x16x32_f16 v[18:21], v[152:155], v[216:219], 0
	v_mfma_f32_16x16x32_f16 v[10:13], v[130:133], v[224:227], 0
	v_mfma_f32_16x16x32_f16 v[6:9], v[152:155], v[224:227], 0
	v_mfma_f32_16x16x32_f16 v[58:61], v[134:137], v[204:207], v[58:61]
	v_mfma_f32_16x16x32_f16 v[50:53], v[156:159], v[204:207], v[50:53]
	v_mfma_f32_16x16x32_f16 v[42:45], v[134:137], v[212:215], v[42:45]
	v_mfma_f32_16x16x32_f16 v[34:37], v[156:159], v[212:215], v[34:37]
	v_mfma_f32_16x16x32_f16 v[26:29], v[134:137], v[220:223], v[26:29]
	v_mfma_f32_16x16x32_f16 v[18:21], v[156:159], v[220:223], v[18:21]
	v_mfma_f32_16x16x32_f16 v[10:13], v[134:137], v[228:231], v[10:13]
	v_mfma_f32_16x16x32_f16 v[6:9], v[156:159], v[228:231], v[6:9]
	v_mfma_f32_16x16x32_f16 v[62:65], v[160:163], v[192:195], 0
	v_mfma_f32_16x16x32_f16 v[54:57], v[184:187], v[192:195], 0
	v_mfma_f32_16x16x32_f16 v[46:49], v[160:163], v[208:211], 0
	v_mfma_f32_16x16x32_f16 v[38:41], v[184:187], v[208:211], 0
	v_mfma_f32_16x16x32_f16 v[30:33], v[160:163], v[216:219], 0
	v_mfma_f32_16x16x32_f16 v[22:25], v[184:187], v[216:219], 0
	v_mfma_f32_16x16x32_f16 v[14:17], v[160:163], v[224:227], 0
	v_mfma_f32_16x16x32_f16 v[2:5], v[184:187], v[224:227], 0
	v_mfma_f32_16x16x32_f16 v[62:65], v[166:169], v[204:207], v[62:65]
	v_mfma_f32_16x16x32_f16 v[54:57], v[188:191], v[204:207], v[54:57]
	v_mfma_f32_16x16x32_f16 v[46:49], v[166:169], v[212:215], v[46:49]
	v_mfma_f32_16x16x32_f16 v[38:41], v[188:191], v[212:215], v[38:41]
	v_mfma_f32_16x16x32_f16 v[30:33], v[166:169], v[220:223], v[30:33]
	v_mfma_f32_16x16x32_f16 v[22:25], v[188:191], v[220:223], v[22:25]
	v_mfma_f32_16x16x32_f16 v[14:17], v[166:169], v[228:231], v[14:17]
	v_mfma_f32_16x16x32_f16 v[2:5], v[188:191], v[228:231], v[2:5]
	s_barrier
; #define PG8_STAGE(bufoff, gbase, voff) do { _Pragma("unroll") for (int _i = 0; _i < 2; ++_i) \
;         __builtin_amdgcn_global_load_lds((const unsigned*)((const char*)(gbase) + (voff)[_i]), (PG8_LAS unsigned*)(lds + (bufoff) + ldsw + _i * 8192), 16, 0, 0); } while (0)
; #define PG8_LDA(dst, b, h) do { _Pragma("unroll") for (int m = 0; m < 4; ++m) _Pragma("unroll") for (int k = 0; k < 2; ++k) dst[m][k] = *(const PG8_LAS bf16x8*)(lds + PG8_SA(b, h) + aoff + m * 2048 + k * 1024); } while (0)
; #define PG8_LDB(dst, b, h) do { _Pragma("unroll") for (int n = 0; n < 2; ++n) _Pragma("unroll") for (int k = 0; k < 2; ++k) dst[n][k] = *(const PG8_LAS bf16x8*)(lds + PG8_SB(b, h) + boff + n * 2048 + k * 1024); } while (0)
; #define PG8_WAIT_V(n) asm volatile("s_waitcnt vmcnt(" #n ")" ::: "memory")
; #define PG8_WAIT_L(n) asm volatile("s_waitcnt lgkmcnt(" #n ")" ::: "memory")
; #define PG8_BAR __builtin_amdgcn_s_barrier()
; #define PG8_SCHED __builtin_amdgcn_sched_barrier(0)
; template <class Epi, class Sched, bool ALIGN_EPI = false, bool SP2 = false, bool F16 = false>
; __device__ __forceinline__ void gemm_phase(PG8_LAS unsigned char* lds, const Gemm g, const Sched& S, const Epi& E) {
;     ...
;             PG8_LDB(B0, 1, 0); PG8_LDB(B1, 1, 1); PG8_SCHED; PG8_LDA(At, 1, 0); PG8_STAGE(PG8_SA(0, 1), a2 + hstepA, voffA);
;             PG8_WAIT_V(8); PG8_WAIT_L(0); PG8_BAR; PG8_MMA(0, 0, At, B0); PG8_MMA(0, 1, At, B1); PG8_BAR; PG8_SCHED;
;             PG8_LDA(At, 1, 1); PG8_STAGE(PG8_SB(1, 0), b3, voffB); PG8_STAGE(PG8_SB(1, 1), b3 + hstepB, voffB); PG8_STAGE(PG8_SA(1, 0), a3, voffA);
;             PG8_WAIT_V(8); PG8_WAIT_L(0); PG8_BAR; PG8_MMA(1, 0, At, B0); PG8_MMA(1, 1, At, B1); PG8_BAR; PG8_SCHED;
	s_setprio 0
	s_add_i32 s83, 0, 0x18000
	s_add_i32 s94, 0, 0x1c000
	ds_read_b128 v[130:133], v143
	ds_read_b128 v[134:137], v143 offset:1024
	ds_read_b128 v[152:155], v143 offset:2048
	ds_read_b128 v[156:159], v143 offset:3072
	ds_read_b128 v[160:163], v145
	ds_read_b128 v[166:169], v145 offset:1024
	ds_read_b128 v[184:187], v145 offset:2048
	ds_read_b128 v[188:191], v145 offset:3072
	s_add_u32 s54, s54, s8
	s_addc_u32 s55, s55, 0
	s_mov_b32 m0, s12
	ds_read_b128 v[192:195], v183 offset:32768
	ds_read_b128 v[204:207], v183 offset:33792
	ds_read_b128 v[208:211], v183 offset:34816
	ds_read_b128 v[212:215], v183 offset:35840
	ds_read_b128 v[216:219], v183 offset:36864
	ds_read_b128 v[220:223], v183 offset:37888
	ds_read_b128 v[224:227], v183 offset:38912
	ds_read_b128 v[228:231], v183 offset:39936
	global_load_lds_dwordx4 v144, s[54:55]
	s_mov_b32 m0, s13
	s_nop 0
	global_load_lds_dwordx4 v140, s[54:55]
	s_waitcnt vmcnt(8)
	s_waitcnt lgkmcnt(0)
	s_setprio 1
	s_barrier
	v_mfma_f32_16x16x32_f16 v[122:125], v[130:133], v[192:195], v[122:125]
	v_mfma_f32_16x16x32_f16 v[114:117], v[152:155], v[192:195], v[114:117]
	v_mfma_f32_16x16x32_f16 v[106:109], v[130:133], v[208:211], v[106:109]
	v_mfma_f32_16x16x32_f16 v[98:101], v[152:155], v[208:211], v[98:101]
	v_mfma_f32_16x16x32_f16 v[90:93], v[130:133], v[216:219], v[90:93]
	v_mfma_f32_16x16x32_f16 v[82:85], v[152:155], v[216:219], v[82:85]
	v_mfma_f32_16x16x32_f16 v[74:77], v[130:133], v[224:227], v[74:77]
	v_mfma_f32_16x16x32_f16 v[66:69], v[152:155], v[224:227], v[66:69]
	v_mfma_f32_16x16x32_f16 v[122:125], v[134:137], v[204:207], v[122:125]
	v_mfma_f32_16x16x32_f16 v[114:117], v[156:159], v[204:207], v[114:117]
	v_mfma_f32_16x16x32_f16 v[106:109], v[134:137], v[212:215], v[106:109]
	v_mfma_f32_16x16x32_f16 v[98:101], v[156:159], v[212:215], v[98:101]
	v_mfma_f32_16x16x32_f16 v[90:93], v[134:137], v[220:223], v[90:93]
	v_mfma_f32_16x16x32_f16 v[82:85], v[156:159], v[220:223], v[82:85]
	v_mfma_f32_16x16x32_f16 v[74:77], v[134:137], v[228:231], v[74:77]
	v_mfma_f32_16x16x32_f16 v[66:69], v[156:159], v[228:231], v[66:69]
	v_mfma_f32_16x16x32_f16 v[126:129], v[160:163], v[192:195], v[126:129]
	v_mfma_f32_16x16x32_f16 v[118:121], v[184:187], v[192:195], v[118:121]
	v_mfma_f32_16x16x32_f16 v[110:113], v[160:163], v[208:211], v[110:113]
	v_mfma_f32_16x16x32_f16 v[102:105], v[184:187], v[208:211], v[102:105]
	v_mfma_f32_16x16x32_f16 v[94:97], v[160:163], v[216:219], v[94:97]
	v_mfma_f32_16x16x32_f16 v[86:89], v[184:187], v[216:219], v[86:89]
	v_mfma_f32_16x16x32_f16 v[78:81], v[160:163], v[224:227], v[78:81]
	v_mfma_f32_16x16x32_f16 v[70:73], v[184:187], v[224:227], v[70:73]
	v_mfma_f32_16x16x32_f16 v[126:129], v[166:169], v[204:207], v[126:129]
	v_mfma_f32_16x16x32_f16 v[118:121], v[188:191], v[204:207], v[118:121]
	v_mfma_f32_16x16x32_f16 v[110:113], v[166:169], v[212:215], v[110:113]
	v_mfma_f32_16x16x32_f16 v[102:105], v[188:191], v[212:215], v[102:105]
	v_mfma_f32_16x16x32_f16 v[94:97], v[166:169], v[220:223], v[94:97]
	v_mfma_f32_16x16x32_f16 v[86:89], v[188:191], v[220:223], v[86:89]
	v_mfma_f32_16x16x32_f16 v[78:81], v[166:169], v[228:231], v[78:81]
	v_mfma_f32_16x16x32_f16 v[70:73], v[188:191], v[228:231], v[70:73]
	s_barrier
	s_setprio 0
	s_add_i32 s54, s83, s2
	s_add_i32 vcc_hi, s82, -2
	s_cmp_eq_u32 s74, vcc_hi
	s_cselect_b32 s99, s47, s81
	s_cselect_b32 s98, s46, s80
	s_add_u32 s98, s98, s92
	s_addc_u32 s99, s99, s93
	s_mov_b32 m0, s54
	s_nop 0
	global_load_lds_dwordx4 v142, s[98:99]
	ds_read_b128 v[192:195], v183 offset:49152
	ds_read_b128 v[204:207], v183 offset:50176
	ds_read_b128 v[208:211], v183 offset:51200
	ds_read_b128 v[212:215], v183 offset:52224
	ds_read_b128 v[216:219], v183 offset:53248
	ds_read_b128 v[220:223], v183 offset:54272
	ds_read_b128 v[224:227], v183 offset:55296
	ds_read_b128 v[228:231], v183 offset:56320
	s_add_i32 m0, s54, 0x2000
	s_nop 0
	global_load_lds_dwordx4 v138, s[98:99]
	s_add_i32 s54, s94, s2
	s_add_u32 s98, s98, s48
	s_addc_u32 s99, s99, 0
	s_mov_b32 m0, s54
	s_nop 0
	global_load_lds_dwordx4 v142, s[98:99]
	s_add_i32 m0, s54, 0x2000
	s_nop 0
	global_load_lds_dwordx4 v138, s[98:99]
	s_add_u32 s98, s52, 0x80
	s_addc_u32 s99, s53, 0
	s_cmp_eq_u32 s74, vcc_hi
	s_cselect_b32 s99, s39, s99
	s_cselect_b32 s98, s38, s98
	s_add_u32 s98, s98, s92
	s_addc_u32 s99, s99, s93
	s_mov_b32 m0, s35
	s_nop 0
	global_load_lds_dwordx4 v144, s[98:99]
	s_mov_b32 m0, s59
	s_nop 0
	global_load_lds_dwordx4 v140, s[98:99]
	s_waitcnt vmcnt(8)
	s_waitcnt lgkmcnt(0)
	s_setprio 1
	s_barrier
	v_mfma_f32_16x16x32_f16 v[58:61], v[130:133], v[192:195], v[58:61]
	v_mfma_f32_16x16x32_f16 v[50:53], v[152:155], v[192:195], v[50:53]
	v_mfma_f32_16x16x32_f16 v[42:45], v[130:133], v[208:211], v[42:45]
	v_mfma_f32_16x16x32_f16 v[34:37], v[152:155], v[208:211], v[34:37]
	v_mfma_f32_16x16x32_f16 v[26:29], v[130:133], v[216:219], v[26:29]
	v_mfma_f32_16x16x32_f16 v[18:21], v[152:155], v[216:219], v[18:21]
	v_mfma_f32_16x16x32_f16 v[10:13], v[130:133], v[224:227], v[10:13]
	v_mfma_f32_16x16x32_f16 v[6:9], v[152:155], v[224:227], v[6:9]
	v_mfma_f32_16x16x32_f16 v[58:61], v[134:137], v[204:207], v[58:61]
	v_mfma_f32_16x16x32_f16 v[50:53], v[156:159], v[204:207], v[50:53]
	v_mfma_f32_16x16x32_f16 v[42:45], v[134:137], v[212:215], v[42:45]
	v_mfma_f32_16x16x32_f16 v[34:37], v[156:159], v[212:215], v[34:37]
	v_mfma_f32_16x16x32_f16 v[26:29], v[134:137], v[220:223], v[26:29]
	v_mfma_f32_16x16x32_f16 v[18:21], v[156:159], v[220:223], v[18:21]
	v_mfma_f32_16x16x32_f16 v[10:13], v[134:137], v[228:231], v[10:13]
	v_mfma_f32_16x16x32_f16 v[6:9], v[156:159], v[228:231], v[6:9]
	v_mfma_f32_16x16x32_f16 v[62:65], v[160:163], v[192:195], v[62:65]
	v_mfma_f32_16x16x32_f16 v[54:57], v[184:187], v[192:195], v[54:57]
	v_mfma_f32_16x16x32_f16 v[46:49], v[160:163], v[208:211], v[46:49]
	v_mfma_f32_16x16x32_f16 v[38:41], v[184:187], v[208:211], v[38:41]
	v_mfma_f32_16x16x32_f16 v[30:33], v[160:163], v[216:219], v[30:33]
	v_mfma_f32_16x16x32_f16 v[22:25], v[184:187], v[216:219], v[22:25]
	v_mfma_f32_16x16x32_f16 v[14:17], v[160:163], v[224:227], v[14:17]
	v_mfma_f32_16x16x32_f16 v[2:5], v[184:187], v[224:227], v[2:5]
	v_mfma_f32_16x16x32_f16 v[62:65], v[166:169], v[204:207], v[62:65]
	v_mfma_f32_16x16x32_f16 v[54:57], v[188:191], v[204:207], v[54:57]
	v_mfma_f32_16x16x32_f16 v[46:49], v[166:169], v[212:215], v[46:49]
	v_mfma_f32_16x16x32_f16 v[38:41], v[188:191], v[212:215], v[38:41]
	v_mfma_f32_16x16x32_f16 v[30:33], v[166:169], v[220:223], v[30:33]
	v_mfma_f32_16x16x32_f16 v[22:25], v[188:191], v[220:223], v[22:25]
	v_mfma_f32_16x16x32_f16 v[14:17], v[166:169], v[228:231], v[14:17]
	v_mfma_f32_16x16x32_f16 v[2:5], v[188:191], v[228:231], v[2:5]
	s_barrier
	s_setprio 0
	s_add_u32 s52, s52, 0x100
	s_addc_u32 s53, s53, 0
	s_add_u32 s80, s80, 0x100
	s_addc_u32 s81, s81, 0
	s_cmp_ge_u32 s82, s65
	s_mov_b32 s54, s82
	s_cbranch_scc1 .LBB0_311

; #define PG8_BAR __builtin_amdgcn_s_barrier()
; template <class Epi, class Sched, bool ALIGN_EPI = false, bool SP2 = false, bool F16 = false>
; __device__ __forceinline__ void gemm_phase(PG8_LAS unsigned char* lds, const Gemm g, const Sched& S, const Epi& E) {
;     ...
;         if constexpr (ALIGN_EPI) { if (wr == 0) PG8_BAR; }
;         if constexpr (!Epi::AFTER_DRAIN) { E(acc, cur, wr, wc, fr, fq); S.done(cur); }
.LBB0_313:
	s_cmp_lg_u64 s[40:41], 0
	s_cbranch_scc0 .Lep_gu
	s_setprio 1

; #define PG8_WAIT_V(n) asm volatile("s_waitcnt vmcnt(" #n ")" ::: "memory")
; #define PG8_BAR __builtin_amdgcn_s_barrier()
; template <class Epi, class Sched, bool ALIGN_EPI = false, bool SP2 = false, bool F16 = false>
; __device__ __forceinline__ void gemm_phase(PG8_LAS unsigned char* lds, const Gemm g, const Sched& S, const Epi& E) {
;     ...
;     PG8_WAIT_V(0);
;     if constexpr (!ALIGN_EPI) { if (wr == 0) PG8_BAR; }
;     PG8_BAR;
.LBB0_320:
	s_setprio 0
	s_waitcnt vmcnt(0)
	v_readlane_b32 s72, v249, 34
	v_readlane_b32 s54, v249, 38
	v_readlane_b32 s73, v249, 35
	v_readlane_b32 s55, v249, 39
	v_readlane_b32 s35, v249, 40
	v_readlane_b32 s75, v249, 41
	s_movk_i32 s59, 0x6000
	s_barrier

; #define PG8_STAGE(bufoff, gbase, voff) do { _Pragma("unroll") for (int _i = 0; _i < 2; ++_i) \
;         __builtin_amdgcn_global_load_lds((const unsigned*)((const char*)(gbase) + (voff)[_i]), (PG8_LAS unsigned*)(lds + (bufoff) + ldsw + _i * 8192), 16, 0, 0); } while (0)
; #define PG8_LDA(dst, b, h) do { _Pragma("unroll") for (int m = 0; m < 4; ++m) _Pragma("unroll") for (int k = 0; k < 2; ++k) dst[m][k] = *(const PG8_LAS bf16x8*)(lds + PG8_SA(b, h) + aoff + m * 2048 + k * 1024); } while (0)
; #define PG8_LDB(dst, b, h) do { _Pragma("unroll") for (int n = 0; n < 2; ++n) _Pragma("unroll") for (int k = 0; k < 2; ++k) dst[n][k] = *(const PG8_LAS bf16x8*)(lds + PG8_SB(b, h) + boff + n * 2048 + k * 1024); } while (0)
; #define PG8_WAIT_V(n) asm volatile("s_waitcnt vmcnt(" #n ")" ::: "memory")
; #define PG8_WAIT_L(n) asm volatile("s_waitcnt lgkmcnt(" #n ")" ::: "memory")
; #define PG8_BAR __builtin_amdgcn_s_barrier()
; #define PG8_SCHED __builtin_amdgcn_sched_barrier(0)
; template <class Epi, class Sched, bool ALIGN_EPI = false, bool SP2 = false, bool F16 = false>
; __device__ __forceinline__ void gemm_phase(PG8_LAS unsigned char* lds, const Gemm g, const Sched& S, const Epi& E) {
;     ...
;             if constexpr (SP2) {
;             PG8_LDB(B0, 0, 0); PG8_LDB(B1, 0, 1); PG8_SCHED; PG8_LDA(At, 0, 0); PG8_STAGE(PG8_SA(1, 1), a1 + hstepA, voffA);
;             PG8_WAIT_V(8); PG8_WAIT_L(0); PG8_BAR; PG8_MMA(0, 0, At, B0); PG8_MMA(0, 1, At, B1); PG8_BAR; PG8_SCHED;
;             PG8_LDA(At, 0, 1); PG8_STAGE(PG8_SB(0, 0), b2, voffB); PG8_STAGE(PG8_SB(0, 1), b2 + hstepB, voffB); PG8_STAGE(PG8_SA(0, 0), a2, voffA);
;             PG8_WAIT_V(8); PG8_WAIT_L(0); PG8_BAR; PG8_MMA(1, 0, At, B0); PG8_MMA(1, 1, At, B1); PG8_BAR; PG8_SCHED;
.Lpk_rs:
	s_setprio 0
	s_add_i32 s81, s54, 2
	s_add_u32 s82, s52, 0x80
	s_addc_u32 s55, s53, 0
	s_add_i32 s94, 0, 0x10000
	s_cmp_eq_u32 s74, s54
	s_cselect_b32 s55, s41, s55
	s_cselect_b32 s54, s40, s82
	s_cselect_b32 s83, s47, s80
	s_cselect_b32 s82, s46, s79
	s_add_i32 s95, 0, 0x14000
	ds_read_b128 v[130:133], v139
	ds_read_b128 v[134:137], v139 offset:1024
	ds_read_b128 v[148:151], v139 offset:2048
	ds_read_b128 v[152:155], v139 offset:3072
	ds_read_b128 v[162:165], v141
	ds_read_b128 v[166:169], v141 offset:1024
	ds_read_b128 v[170:173], v141 offset:2048
	ds_read_b128 v[182:185], v141 offset:3072
	s_add_i32 m0, s3, 0xc000
	ds_read_b128 v[186:189], v160
	ds_read_b128 v[190:193], v160 offset:1024
	ds_read_b128 v[194:197], v160 offset:2048
	ds_read_b128 v[204:207], v160 offset:3072
	ds_read_b128 v[208:211], v160 offset:4096
	ds_read_b128 v[212:215], v160 offset:5120
	ds_read_b128 v[216:219], v160 offset:6144
	ds_read_b128 v[220:223], v160 offset:7168
	global_load_lds_dwordx4 v144, s[52:53]
	s_add_i32 m0, s3, 0xe000
	s_nop 0
	global_load_lds_dwordx4 v146, s[52:53]
	s_waitcnt vmcnt(8)
	s_waitcnt lgkmcnt(0)
	s_setprio 1
	s_barrier
	v_mfma_f32_16x16x32_bf16 v[122:125], v[130:133], v[186:189], 0
	v_mfma_f32_16x16x32_bf16 v[126:129], v[148:151], v[186:189], 0
	v_mfma_f32_16x16x32_bf16 v[110:113], v[130:133], v[194:197], 0
	v_mfma_f32_16x16x32_bf16 v[106:109], v[148:151], v[194:197], 0
	v_mfma_f32_16x16x32_bf16 v[94:97], v[130:133], v[208:211], 0
	v_mfma_f32_16x16x32_bf16 v[90:93], v[148:151], v[208:211], 0
	v_mfma_f32_16x16x32_bf16 v[78:81], v[130:133], v[216:219], 0
	v_mfma_f32_16x16x32_bf16 v[74:77], v[148:151], v[216:219], 0
	v_mfma_f32_16x16x32_bf16 v[122:125], v[134:137], v[190:193], v[122:125]
	v_mfma_f32_16x16x32_bf16 v[126:129], v[152:155], v[190:193], v[126:129]
	v_mfma_f32_16x16x32_bf16 v[110:113], v[134:137], v[204:207], v[110:113]
	v_mfma_f32_16x16x32_bf16 v[106:109], v[152:155], v[204:207], v[106:109]
	v_mfma_f32_16x16x32_bf16 v[94:97], v[134:137], v[212:215], v[94:97]
	v_mfma_f32_16x16x32_bf16 v[90:93], v[152:155], v[212:215], v[90:93]
	v_mfma_f32_16x16x32_bf16 v[78:81], v[134:137], v[220:223], v[78:81]
	v_mfma_f32_16x16x32_bf16 v[74:77], v[152:155], v[220:223], v[74:77]
	v_mfma_f32_16x16x32_bf16 v[118:121], v[162:165], v[186:189], 0
	v_mfma_f32_16x16x32_bf16 v[114:117], v[170:173], v[186:189], 0
	v_mfma_f32_16x16x32_bf16 v[102:105], v[162:165], v[194:197], 0
	v_mfma_f32_16x16x32_bf16 v[98:101], v[170:173], v[194:197], 0
	v_mfma_f32_16x16x32_bf16 v[86:89], v[162:165], v[208:211], 0
	v_mfma_f32_16x16x32_bf16 v[82:85], v[170:173], v[208:211], 0
	v_mfma_f32_16x16x32_bf16 v[70:73], v[162:165], v[216:219], 0
	v_mfma_f32_16x16x32_bf16 v[66:69], v[170:173], v[216:219], 0
	v_mfma_f32_16x16x32_bf16 v[118:121], v[166:169], v[190:193], v[118:121]
	v_mfma_f32_16x16x32_bf16 v[114:117], v[182:185], v[190:193], v[114:117]
	v_mfma_f32_16x16x32_bf16 v[102:105], v[166:169], v[204:207], v[102:105]
	v_mfma_f32_16x16x32_bf16 v[98:101], v[182:185], v[204:207], v[98:101]
	v_mfma_f32_16x16x32_bf16 v[86:89], v[166:169], v[212:215], v[86:89]
	v_mfma_f32_16x16x32_bf16 v[82:85], v[182:185], v[212:215], v[82:85]
	v_mfma_f32_16x16x32_bf16 v[70:73], v[166:169], v[220:223], v[70:73]
	v_mfma_f32_16x16x32_bf16 v[66:69], v[182:185], v[220:223], v[66:69]
	s_barrier
	s_setprio 0
	s_add_i32 s94, s94, s2
	s_mov_b32 m0, s94
	s_nop 0
	global_load_lds_dwordx4 v174, s[82:83]
	ds_read_b128 v[186:189], v160 offset:16384
	ds_read_b128 v[190:193], v160 offset:17408
	ds_read_b128 v[194:197], v160 offset:18432
	ds_read_b128 v[204:207], v160 offset:19456
	ds_read_b128 v[208:211], v160 offset:20480
	ds_read_b128 v[212:215], v160 offset:21504
	ds_read_b128 v[216:219], v160 offset:22528
	ds_read_b128 v[220:223], v160 offset:23552
	s_add_i32 m0, s94, 0x2000
	s_nop 0
	global_load_lds_dwordx4 v142, s[82:83]
	s_add_i32 s94, s95, s2
	s_add_u32 s82, s82, s48
	s_addc_u32 s83, s83, 0
	s_mov_b32 m0, s94
	s_nop 0
	global_load_lds_dwordx4 v174, s[82:83]
	s_add_i32 m0, s94, 0x2000
	s_nop 0
	global_load_lds_dwordx4 v142, s[82:83]
	s_mov_b32 m0, s3
	s_nop 0
	global_load_lds_dwordx4 v138, s[54:55]
	s_mov_b32 m0, s12
	s_nop 0
	global_load_lds_dwordx4 v140, s[54:55]
	s_waitcnt vmcnt(8)
	s_waitcnt lgkmcnt(0)
	s_setprio 1
	s_barrier
	v_mfma_f32_16x16x32_bf16 v[62:65], v[130:133], v[186:189], 0
	v_mfma_f32_16x16x32_bf16 v[58:61], v[148:151], v[186:189], 0
	v_mfma_f32_16x16x32_bf16 v[46:49], v[130:133], v[194:197], 0
	v_mfma_f32_16x16x32_bf16 v[42:45], v[148:151], v[194:197], 0
	v_mfma_f32_16x16x32_bf16 v[30:33], v[130:133], v[208:211], 0
	v_mfma_f32_16x16x32_bf16 v[26:29], v[148:151], v[208:211], 0
	v_mfma_f32_16x16x32_bf16 v[14:17], v[130:133], v[216:219], 0
	v_mfma_f32_16x16x32_bf16 v[10:13], v[148:151], v[216:219], 0
	v_mfma_f32_16x16x32_bf16 v[62:65], v[134:137], v[190:193], v[62:65]
	v_mfma_f32_16x16x32_bf16 v[58:61], v[152:155], v[190:193], v[58:61]
	v_mfma_f32_16x16x32_bf16 v[46:49], v[134:137], v[204:207], v[46:49]
	v_mfma_f32_16x16x32_bf16 v[42:45], v[152:155], v[204:207], v[42:45]
	v_mfma_f32_16x16x32_bf16 v[30:33], v[134:137], v[212:215], v[30:33]
	v_mfma_f32_16x16x32_bf16 v[26:29], v[152:155], v[212:215], v[26:29]
	v_mfma_f32_16x16x32_bf16 v[14:17], v[134:137], v[220:223], v[14:17]
	v_mfma_f32_16x16x32_bf16 v[10:13], v[152:155], v[220:223], v[10:13]
	v_mfma_f32_16x16x32_bf16 v[54:57], v[162:165], v[186:189], 0
	v_mfma_f32_16x16x32_bf16 v[50:53], v[170:173], v[186:189], 0
	v_mfma_f32_16x16x32_bf16 v[38:41], v[162:165], v[194:197], 0
	v_mfma_f32_16x16x32_bf16 v[34:37], v[170:173], v[194:197], 0
	v_mfma_f32_16x16x32_bf16 v[22:25], v[162:165], v[208:211], 0
	v_mfma_f32_16x16x32_bf16 v[18:21], v[170:173], v[208:211], 0
	v_mfma_f32_16x16x32_bf16 v[6:9], v[162:165], v[216:219], 0
	v_mfma_f32_16x16x32_bf16 v[2:5], v[170:173], v[216:219], 0
	v_mfma_f32_16x16x32_bf16 v[54:57], v[166:169], v[190:193], v[54:57]
	v_mfma_f32_16x16x32_bf16 v[50:53], v[182:185], v[190:193], v[50:53]
	v_mfma_f32_16x16x32_bf16 v[38:41], v[166:169], v[204:207], v[38:41]
	v_mfma_f32_16x16x32_bf16 v[34:37], v[182:185], v[204:207], v[34:37]
	v_mfma_f32_16x16x32_bf16 v[22:25], v[166:169], v[212:215], v[22:25]
	v_mfma_f32_16x16x32_bf16 v[18:21], v[182:185], v[212:215], v[18:21]
	v_mfma_f32_16x16x32_bf16 v[6:9], v[166:169], v[220:223], v[6:9]
	v_mfma_f32_16x16x32_bf16 v[2:5], v[182:185], v[220:223], v[2:5]
	s_barrier
; #define PG8_STAGE(bufoff, gbase, voff) do { _Pragma("unroll") for (int _i = 0; _i < 2; ++_i) \
;         __builtin_amdgcn_global_load_lds((const unsigned*)((const char*)(gbase) + (voff)[_i]), (PG8_LAS unsigned*)(lds + (bufoff) + ldsw + _i * 8192), 16, 0, 0); } while (0)
; #define PG8_LDA(dst, b, h) do { _Pragma("unroll") for (int m = 0; m < 4; ++m) _Pragma("unroll") for (int k = 0; k < 2; ++k) dst[m][k] = *(const PG8_LAS bf16x8*)(lds + PG8_SA(b, h) + aoff + m * 2048 + k * 1024); } while (0)
; #define PG8_LDB(dst, b, h) do { _Pragma("unroll") for (int n = 0; n < 2; ++n) _Pragma("unroll") for (int k = 0; k < 2; ++k) dst[n][k] = *(const PG8_LAS bf16x8*)(lds + PG8_SB(b, h) + boff + n * 2048 + k * 1024); } while (0)
; #define PG8_WAIT_V(n) asm volatile("s_waitcnt vmcnt(" #n ")" ::: "memory")
; #define PG8_WAIT_L(n) asm volatile("s_waitcnt lgkmcnt(" #n ")" ::: "memory")
; #define PG8_BAR __builtin_amdgcn_s_barrier()
; #define PG8_SCHED __builtin_amdgcn_sched_barrier(0)
; template <class Epi, class Sched, bool ALIGN_EPI = false, bool SP2 = false, bool F16 = false>
; __device__ __forceinline__ void gemm_phase(PG8_LAS unsigned char* lds, const Gemm g, const Sched& S, const Epi& E) {
;     ...
;             PG8_LDB(B0, 1, 0); PG8_LDB(B1, 1, 1); PG8_SCHED; PG8_LDA(At, 1, 0); PG8_STAGE(PG8_SA(0, 1), a2 + hstepA, voffA);
;             PG8_WAIT_V(8); PG8_WAIT_L(0); PG8_BAR; PG8_MMA(0, 0, At, B0); PG8_MMA(0, 1, At, B1); PG8_BAR; PG8_SCHED;
;             PG8_LDA(At, 1, 1); PG8_STAGE(PG8_SB(1, 0), b3, voffB); PG8_STAGE(PG8_SB(1, 1), b3 + hstepB, voffB); PG8_STAGE(PG8_SA(1, 0), a3, voffA);
;             PG8_WAIT_V(8); PG8_WAIT_L(0); PG8_BAR; PG8_MMA(1, 0, At, B0); PG8_MMA(1, 1, At, B1); PG8_BAR; PG8_SCHED;
	s_setprio 0
	s_add_i32 s82, 0, 0x18000
	s_add_i32 s83, 0, 0x1c000
	ds_read_b128 v[130:133], v143
	ds_read_b128 v[134:137], v143 offset:1024
	ds_read_b128 v[148:151], v143 offset:2048
	ds_read_b128 v[152:155], v143 offset:3072
	ds_read_b128 v[162:165], v157
	ds_read_b128 v[166:169], v157 offset:1024
	ds_read_b128 v[170:173], v157 offset:2048
	ds_read_b128 v[182:185], v157 offset:3072
	s_add_u32 s54, s54, s8
	s_addc_u32 s55, s55, 0
	s_mov_b32 m0, s13
	ds_read_b128 v[186:189], v160 offset:32768
	ds_read_b128 v[190:193], v160 offset:33792
	ds_read_b128 v[194:197], v160 offset:34816
	ds_read_b128 v[204:207], v160 offset:35840
	ds_read_b128 v[208:211], v160 offset:36864
	ds_read_b128 v[212:215], v160 offset:37888
	ds_read_b128 v[216:219], v160 offset:38912
	ds_read_b128 v[220:223], v160 offset:39936
	global_load_lds_dwordx4 v138, s[54:55]
	s_mov_b32 m0, s22
	s_nop 0
	global_load_lds_dwordx4 v140, s[54:55]
	s_waitcnt vmcnt(8)
	s_waitcnt lgkmcnt(0)
	s_setprio 1
	s_barrier
	v_mfma_f32_16x16x32_bf16 v[122:125], v[130:133], v[186:189], v[122:125]
	v_mfma_f32_16x16x32_bf16 v[126:129], v[148:151], v[186:189], v[126:129]
	v_mfma_f32_16x16x32_bf16 v[110:113], v[130:133], v[194:197], v[110:113]
	v_mfma_f32_16x16x32_bf16 v[106:109], v[148:151], v[194:197], v[106:109]
	v_mfma_f32_16x16x32_bf16 v[94:97], v[130:133], v[208:211], v[94:97]
	v_mfma_f32_16x16x32_bf16 v[90:93], v[148:151], v[208:211], v[90:93]
	v_mfma_f32_16x16x32_bf16 v[78:81], v[130:133], v[216:219], v[78:81]
	v_mfma_f32_16x16x32_bf16 v[74:77], v[148:151], v[216:219], v[74:77]
	v_mfma_f32_16x16x32_bf16 v[122:125], v[134:137], v[190:193], v[122:125]
	v_mfma_f32_16x16x32_bf16 v[126:129], v[152:155], v[190:193], v[126:129]
	v_mfma_f32_16x16x32_bf16 v[110:113], v[134:137], v[204:207], v[110:113]
	v_mfma_f32_16x16x32_bf16 v[106:109], v[152:155], v[204:207], v[106:109]
	v_mfma_f32_16x16x32_bf16 v[94:97], v[134:137], v[212:215], v[94:97]
	v_mfma_f32_16x16x32_bf16 v[90:93], v[152:155], v[212:215], v[90:93]
	v_mfma_f32_16x16x32_bf16 v[78:81], v[134:137], v[220:223], v[78:81]
	v_mfma_f32_16x16x32_bf16 v[74:77], v[152:155], v[220:223], v[74:77]
	v_mfma_f32_16x16x32_bf16 v[118:121], v[162:165], v[186:189], v[118:121]
	v_mfma_f32_16x16x32_bf16 v[114:117], v[170:173], v[186:189], v[114:117]
	v_mfma_f32_16x16x32_bf16 v[102:105], v[162:165], v[194:197], v[102:105]
	v_mfma_f32_16x16x32_bf16 v[98:101], v[170:173], v[194:197], v[98:101]
	v_mfma_f32_16x16x32_bf16 v[86:89], v[162:165], v[208:211], v[86:89]
	v_mfma_f32_16x16x32_bf16 v[82:85], v[170:173], v[208:211], v[82:85]
	v_mfma_f32_16x16x32_bf16 v[70:73], v[162:165], v[216:219], v[70:73]
	v_mfma_f32_16x16x32_bf16 v[66:69], v[170:173], v[216:219], v[66:69]
	v_mfma_f32_16x16x32_bf16 v[118:121], v[166:169], v[190:193], v[118:121]
	v_mfma_f32_16x16x32_bf16 v[114:117], v[182:185], v[190:193], v[114:117]
	v_mfma_f32_16x16x32_bf16 v[102:105], v[166:169], v[204:207], v[102:105]
	v_mfma_f32_16x16x32_bf16 v[98:101], v[182:185], v[204:207], v[98:101]
	v_mfma_f32_16x16x32_bf16 v[86:89], v[166:169], v[212:215], v[86:89]
	v_mfma_f32_16x16x32_bf16 v[82:85], v[182:185], v[212:215], v[82:85]
	v_mfma_f32_16x16x32_bf16 v[70:73], v[166:169], v[220:223], v[70:73]
	v_mfma_f32_16x16x32_bf16 v[66:69], v[182:185], v[220:223], v[66:69]
	s_barrier
	s_setprio 0
	s_add_i32 s54, s82, s2
	s_add_i32 vcc_hi, s81, -2
	s_cmp_eq_u32 s74, vcc_hi
	s_cselect_b32 s99, s47, s80
	s_cselect_b32 s98, s46, s79
	s_add_u32 s98, s98, s92
	s_addc_u32 s99, s99, s93
	s_mov_b32 m0, s54
	s_nop 0
	global_load_lds_dwordx4 v174, s[98:99]
	ds_read_b128 v[186:189], v160 offset:49152
	ds_read_b128 v[190:193], v160 offset:50176
	ds_read_b128 v[194:197], v160 offset:51200
	ds_read_b128 v[204:207], v160 offset:52224
	ds_read_b128 v[208:211], v160 offset:53248
	ds_read_b128 v[212:215], v160 offset:54272
	ds_read_b128 v[216:219], v160 offset:55296
	ds_read_b128 v[220:223], v160 offset:56320
	s_add_i32 m0, s54, 0x2000
	s_nop 0
	global_load_lds_dwordx4 v142, s[98:99]
	s_add_i32 s54, s83, s2
	s_add_u32 s98, s98, s48
	s_addc_u32 s99, s99, 0
	s_mov_b32 m0, s54
	s_nop 0
	global_load_lds_dwordx4 v174, s[98:99]
	s_add_i32 m0, s54, 0x2000
	s_nop 0
	global_load_lds_dwordx4 v142, s[98:99]
	s_add_u32 s98, s52, 0x80
	s_addc_u32 s99, s53, 0
	s_cmp_eq_u32 s74, vcc_hi
	s_cselect_b32 s99, s41, s99
	s_cselect_b32 s98, s40, s98
	s_add_u32 s98, s98, s92
	s_addc_u32 s99, s99, s93
	s_mov_b32 m0, s33
	s_nop 0
	global_load_lds_dwordx4 v138, s[98:99]
	s_mov_b32 m0, s35
	s_nop 0
	global_load_lds_dwordx4 v140, s[98:99]
	s_waitcnt vmcnt(8)
	s_waitcnt lgkmcnt(0)
	s_setprio 1
	s_barrier
	v_mfma_f32_16x16x32_bf16 v[62:65], v[130:133], v[186:189], v[62:65]
	v_mfma_f32_16x16x32_bf16 v[58:61], v[148:151], v[186:189], v[58:61]
	v_mfma_f32_16x16x32_bf16 v[46:49], v[130:133], v[194:197], v[46:49]
	v_mfma_f32_16x16x32_bf16 v[42:45], v[148:151], v[194:197], v[42:45]
	v_mfma_f32_16x16x32_bf16 v[30:33], v[130:133], v[208:211], v[30:33]
	v_mfma_f32_16x16x32_bf16 v[26:29], v[148:151], v[208:211], v[26:29]
	v_mfma_f32_16x16x32_bf16 v[14:17], v[130:133], v[216:219], v[14:17]
	v_mfma_f32_16x16x32_bf16 v[10:13], v[148:151], v[216:219], v[10:13]
	v_mfma_f32_16x16x32_bf16 v[62:65], v[134:137], v[190:193], v[62:65]
	v_mfma_f32_16x16x32_bf16 v[58:61], v[152:155], v[190:193], v[58:61]
	v_mfma_f32_16x16x32_bf16 v[46:49], v[134:137], v[204:207], v[46:49]
	v_mfma_f32_16x16x32_bf16 v[42:45], v[152:155], v[204:207], v[42:45]
	v_mfma_f32_16x16x32_bf16 v[30:33], v[134:137], v[212:215], v[30:33]
	v_mfma_f32_16x16x32_bf16 v[26:29], v[152:155], v[212:215], v[26:29]
	v_mfma_f32_16x16x32_bf16 v[14:17], v[134:137], v[220:223], v[14:17]
	v_mfma_f32_16x16x32_bf16 v[10:13], v[152:155], v[220:223], v[10:13]
	v_mfma_f32_16x16x32_bf16 v[54:57], v[162:165], v[186:189], v[54:57]
	v_mfma_f32_16x16x32_bf16 v[50:53], v[170:173], v[186:189], v[50:53]
	v_mfma_f32_16x16x32_bf16 v[38:41], v[162:165], v[194:197], v[38:41]
	v_mfma_f32_16x16x32_bf16 v[34:37], v[170:173], v[194:197], v[34:37]
	v_mfma_f32_16x16x32_bf16 v[22:25], v[162:165], v[208:211], v[22:25]
	v_mfma_f32_16x16x32_bf16 v[18:21], v[170:173], v[208:211], v[18:21]
	v_mfma_f32_16x16x32_bf16 v[6:9], v[162:165], v[216:219], v[6:9]
	v_mfma_f32_16x16x32_bf16 v[2:5], v[170:173], v[216:219], v[2:5]
	v_mfma_f32_16x16x32_bf16 v[54:57], v[166:169], v[190:193], v[54:57]
	v_mfma_f32_16x16x32_bf16 v[50:53], v[182:185], v[190:193], v[50:53]
	v_mfma_f32_16x16x32_bf16 v[38:41], v[166:169], v[204:207], v[38:41]
	v_mfma_f32_16x16x32_bf16 v[34:37], v[182:185], v[204:207], v[34:37]
	v_mfma_f32_16x16x32_bf16 v[22:25], v[166:169], v[212:215], v[22:25]
	v_mfma_f32_16x16x32_bf16 v[18:21], v[182:185], v[212:215], v[18:21]
	v_mfma_f32_16x16x32_bf16 v[6:9], v[166:169], v[220:223], v[6:9]
	v_mfma_f32_16x16x32_bf16 v[2:5], v[182:185], v[220:223], v[2:5]
	s_barrier
	s_setprio 0
	s_add_u32 s52, s52, 0x100
	s_addc_u32 s53, s53, 0
	s_add_u32 s79, s79, 0x100
	s_addc_u32 s80, s80, 0
	s_cmp_ge_u32 s81, s65
	s_mov_b32 s54, s81
	s_cbranch_scc1 .LBB0_346

; #define PG8_BAR __builtin_amdgcn_s_barrier()
; template <class Epi, class Sched, bool ALIGN_EPI = false, bool SP2 = false, bool F16 = false>
; __device__ __forceinline__ void gemm_phase(PG8_LAS unsigned char* lds, const Gemm g, const Sched& S, const Epi& E) {
;     ...
;         if constexpr (ALIGN_EPI) { if (wr == 0) PG8_BAR; }
;         if constexpr (!Epi::AFTER_DRAIN) { E(acc, cur, wr, wc, fr, fq); S.done(cur); }
.LBB0_348:
	s_cmp_lg_u64 s[16:17], 0
	s_cbranch_scc0 .Lep_rs
	s_setprio 1

; #define PG8_STAGE(bufoff, gbase, voff) do { _Pragma("unroll") for (int _i = 0; _i < 2; ++_i) \
;         __builtin_amdgcn_global_load_lds((const unsigned*)((const char*)(gbase) + (voff)[_i]), (PG8_LAS unsigned*)(lds + (bufoff) + ldsw + _i * 8192), 16, 0, 0); } while (0)
; #define PG8_LDA(dst, b, h) do { _Pragma("unroll") for (int m = 0; m < 4; ++m) _Pragma("unroll") for (int k = 0; k < 2; ++k) dst[m][k] = *(const PG8_LAS bf16x8*)(lds + PG8_SA(b, h) + aoff + m * 2048 + k * 1024); } while (0)
; #define PG8_LDB(dst, b, h) do { _Pragma("unroll") for (int n = 0; n < 2; ++n) _Pragma("unroll") for (int k = 0; k < 2; ++k) dst[n][k] = *(const PG8_LAS bf16x8*)(lds + PG8_SB(b, h) + boff + n * 2048 + k * 1024); } while (0)
; #define PG8_WAIT_V(n) asm volatile("s_waitcnt vmcnt(" #n ")" ::: "memory")
; #define PG8_WAIT_L(n) asm volatile("s_waitcnt lgkmcnt(" #n ")" ::: "memory")
; #define PG8_BAR __builtin_amdgcn_s_barrier()
; #define PG8_SCHED __builtin_amdgcn_sched_barrier(0)
; template <class Epi, class Sched, bool ALIGN_EPI = false, bool SP2 = false, bool F16 = false>
; __device__ __forceinline__ void gemm_phase(PG8_LAS unsigned char* lds, const Gemm g, const Sched& S, const Epi& E) {
;     ...
;             if constexpr (SP2) {
;             PG8_LDB(B0, 0, 0); PG8_LDB(B1, 0, 1); PG8_SCHED; PG8_LDA(At, 0, 0); PG8_STAGE(PG8_SA(1, 1), a1 + hstepA, voffA);
;             PG8_WAIT_V(8); PG8_WAIT_L(0); PG8_BAR; PG8_MMA(0, 0, At, B0); PG8_MMA(0, 1, At, B1); PG8_BAR; PG8_SCHED;
;             PG8_LDA(At, 0, 1); PG8_STAGE(PG8_SB(0, 0), b2, voffB); PG8_STAGE(PG8_SB(0, 1), b2 + hstepB, voffB); PG8_STAGE(PG8_SA(0, 0), a2, voffA);
;             PG8_WAIT_V(8); PG8_WAIT_L(0); PG8_BAR; PG8_MMA(1, 0, At, B0); PG8_MMA(1, 1, At, B1); PG8_BAR; PG8_SCHED;
.Lpk_bf:
	s_setprio 0
	s_add_i32 s78, s72, 2
	s_add_u32 s79, s46, 0x80
	s_addc_u32 s73, s47, 0
	s_add_i32 vcc_lo, 0, 0x10000
	s_cmp_eq_u32 s74, s72
	s_cselect_b32 s73, s55, s73
	s_cselect_b32 s72, s54, s79
	s_cselect_b32 s95, s53, s24
	s_cselect_b32 s94, s52, s13
	s_add_i32 s79, 0, 0x14000
	ds_read_b128 v[130:133], v155
	ds_read_b128 v[134:137], v155 offset:1024
	ds_read_b128 v[138:141], v155 offset:2048
	ds_read_b128 v[142:145], v155 offset:3072
	ds_read_b128 v[146:149], v157
	ds_read_b128 v[150:153], v157 offset:1024
	ds_read_b128 v[182:185], v157 offset:2048
	ds_read_b128 v[186:189], v157 offset:3072
	s_add_i32 m0, s36, 0xc000
	ds_read_b128 v[190:193], v204
	ds_read_b128 v[194:197], v204 offset:1024
	ds_read_b128 v[206:209], v204 offset:2048
	ds_read_b128 v[210:213], v204 offset:3072
	ds_read_b128 v[214:217], v204 offset:4096
	ds_read_b128 v[218:221], v204 offset:5120
	ds_read_b128 v[222:225], v204 offset:6144
	ds_read_b128 v[226:229], v204 offset:7168
	global_load_lds_dwordx4 v168, s[46:47]
	s_add_i32 m0, s36, 0xe000
	s_nop 0
	global_load_lds_dwordx4 v170, s[46:47]
	s_waitcnt vmcnt(8)
	s_waitcnt lgkmcnt(0)
	s_setprio 1
	s_barrier
	v_mfma_f32_16x16x32_bf16 v[122:125], v[130:133], v[190:193], 0
	v_mfma_f32_16x16x32_bf16 v[126:129], v[138:141], v[190:193], 0
	v_mfma_f32_16x16x32_bf16 v[110:113], v[130:133], v[206:209], 0
	v_mfma_f32_16x16x32_bf16 v[106:109], v[138:141], v[206:209], 0
	v_mfma_f32_16x16x32_bf16 v[94:97], v[130:133], v[214:217], 0
	v_mfma_f32_16x16x32_bf16 v[90:93], v[138:141], v[214:217], 0
	v_mfma_f32_16x16x32_bf16 v[78:81], v[130:133], v[222:225], 0
	v_mfma_f32_16x16x32_bf16 v[74:77], v[138:141], v[222:225], 0
	v_mfma_f32_16x16x32_bf16 v[122:125], v[134:137], v[194:197], v[122:125]
	v_mfma_f32_16x16x32_bf16 v[126:129], v[142:145], v[194:197], v[126:129]
	v_mfma_f32_16x16x32_bf16 v[110:113], v[134:137], v[210:213], v[110:113]
	v_mfma_f32_16x16x32_bf16 v[106:109], v[142:145], v[210:213], v[106:109]
	v_mfma_f32_16x16x32_bf16 v[94:97], v[134:137], v[218:221], v[94:97]
	v_mfma_f32_16x16x32_bf16 v[90:93], v[142:145], v[218:221], v[90:93]
	v_mfma_f32_16x16x32_bf16 v[78:81], v[134:137], v[226:229], v[78:81]
	v_mfma_f32_16x16x32_bf16 v[74:77], v[142:145], v[226:229], v[74:77]
	v_mfma_f32_16x16x32_bf16 v[118:121], v[146:149], v[190:193], 0
	v_mfma_f32_16x16x32_bf16 v[114:117], v[182:185], v[190:193], 0
	v_mfma_f32_16x16x32_bf16 v[102:105], v[146:149], v[206:209], 0
	v_mfma_f32_16x16x32_bf16 v[98:101], v[182:185], v[206:209], 0
	v_mfma_f32_16x16x32_bf16 v[86:89], v[146:149], v[214:217], 0
	v_mfma_f32_16x16x32_bf16 v[82:85], v[182:185], v[214:217], 0
	v_mfma_f32_16x16x32_bf16 v[70:73], v[146:149], v[222:225], 0
	v_mfma_f32_16x16x32_bf16 v[66:69], v[182:185], v[222:225], 0
	v_mfma_f32_16x16x32_bf16 v[118:121], v[150:153], v[194:197], v[118:121]
	v_mfma_f32_16x16x32_bf16 v[114:117], v[186:189], v[194:197], v[114:117]
	v_mfma_f32_16x16x32_bf16 v[102:105], v[150:153], v[210:213], v[102:105]
	v_mfma_f32_16x16x32_bf16 v[98:101], v[186:189], v[210:213], v[98:101]
	v_mfma_f32_16x16x32_bf16 v[86:89], v[150:153], v[218:221], v[86:89]
	v_mfma_f32_16x16x32_bf16 v[82:85], v[186:189], v[218:221], v[82:85]
	v_mfma_f32_16x16x32_bf16 v[70:73], v[150:153], v[226:229], v[70:73]
	v_mfma_f32_16x16x32_bf16 v[66:69], v[186:189], v[226:229], v[66:69]
	s_barrier
	s_setprio 0
	s_add_i32 vcc_lo, vcc_lo, s75
	s_mov_b32 m0, vcc_lo
	s_nop 0
	global_load_lds_dwordx4 v156, s[94:95]
	ds_read_b128 v[190:193], v204 offset:16384
	ds_read_b128 v[194:197], v204 offset:17408
	ds_read_b128 v[206:209], v204 offset:18432
	ds_read_b128 v[210:213], v204 offset:19456
	ds_read_b128 v[214:217], v204 offset:20480
	ds_read_b128 v[218:221], v204 offset:21504
	ds_read_b128 v[222:225], v204 offset:22528
	ds_read_b128 v[226:229], v204 offset:23552
	s_add_i32 m0, vcc_lo, 0x2000
	s_nop 0
	global_load_lds_dwordx4 v160, s[94:95]
	s_add_i32 s79, s79, s75
	s_add_u32 s94, s94, s48
	s_addc_u32 s95, s95, 0
	s_mov_b32 m0, s79
	s_nop 0
	global_load_lds_dwordx4 v156, s[94:95]
	s_add_i32 m0, s79, 0x2000
	s_nop 0
	global_load_lds_dwordx4 v160, s[94:95]
	s_mov_b32 m0, s36
	s_nop 0
	global_load_lds_dwordx4 v154, s[72:73]
	s_mov_b32 m0, s37
	s_nop 0
	global_load_lds_dwordx4 v158, s[72:73]
	s_waitcnt vmcnt(8)
	s_waitcnt lgkmcnt(0)
	s_setprio 1
	s_barrier
	v_mfma_f32_16x16x32_bf16 v[62:65], v[130:133], v[190:193], 0
	v_mfma_f32_16x16x32_bf16 v[58:61], v[138:141], v[190:193], 0
	v_mfma_f32_16x16x32_bf16 v[46:49], v[130:133], v[206:209], 0
	v_mfma_f32_16x16x32_bf16 v[42:45], v[138:141], v[206:209], 0
	v_mfma_f32_16x16x32_bf16 v[30:33], v[130:133], v[214:217], 0
	v_mfma_f32_16x16x32_bf16 v[26:29], v[138:141], v[214:217], 0
	v_mfma_f32_16x16x32_bf16 v[14:17], v[130:133], v[222:225], 0
	v_mfma_f32_16x16x32_bf16 v[10:13], v[138:141], v[222:225], 0
	v_mfma_f32_16x16x32_bf16 v[62:65], v[134:137], v[194:197], v[62:65]
	v_mfma_f32_16x16x32_bf16 v[58:61], v[142:145], v[194:197], v[58:61]
	v_mfma_f32_16x16x32_bf16 v[46:49], v[134:137], v[210:213], v[46:49]
	v_mfma_f32_16x16x32_bf16 v[42:45], v[142:145], v[210:213], v[42:45]
	v_mfma_f32_16x16x32_bf16 v[30:33], v[134:137], v[218:221], v[30:33]
	v_mfma_f32_16x16x32_bf16 v[26:29], v[142:145], v[218:221], v[26:29]
	v_mfma_f32_16x16x32_bf16 v[14:17], v[134:137], v[226:229], v[14:17]
	v_mfma_f32_16x16x32_bf16 v[10:13], v[142:145], v[226:229], v[10:13]
	v_mfma_f32_16x16x32_bf16 v[54:57], v[146:149], v[190:193], 0
	v_mfma_f32_16x16x32_bf16 v[50:53], v[182:185], v[190:193], 0
	v_mfma_f32_16x16x32_bf16 v[38:41], v[146:149], v[206:209], 0
	v_mfma_f32_16x16x32_bf16 v[34:37], v[182:185], v[206:209], 0
	v_mfma_f32_16x16x32_bf16 v[22:25], v[146:149], v[214:217], 0
	v_mfma_f32_16x16x32_bf16 v[18:21], v[182:185], v[214:217], 0
	v_mfma_f32_16x16x32_bf16 v[6:9], v[146:149], v[222:225], 0
	v_mfma_f32_16x16x32_bf16 v[2:5], v[182:185], v[222:225], 0
	v_mfma_f32_16x16x32_bf16 v[54:57], v[150:153], v[194:197], v[54:57]
	v_mfma_f32_16x16x32_bf16 v[50:53], v[186:189], v[194:197], v[50:53]
	v_mfma_f32_16x16x32_bf16 v[38:41], v[150:153], v[210:213], v[38:41]
	v_mfma_f32_16x16x32_bf16 v[34:37], v[186:189], v[210:213], v[34:37]
	v_mfma_f32_16x16x32_bf16 v[22:25], v[150:153], v[218:221], v[22:25]
	v_mfma_f32_16x16x32_bf16 v[18:21], v[186:189], v[218:221], v[18:21]
	v_mfma_f32_16x16x32_bf16 v[6:9], v[150:153], v[226:229], v[6:9]
	v_mfma_f32_16x16x32_bf16 v[2:5], v[186:189], v[226:229], v[2:5]
	s_barrier
; #define PG8_STAGE(bufoff, gbase, voff) do { _Pragma("unroll") for (int _i = 0; _i < 2; ++_i) \
;         __builtin_amdgcn_global_load_lds((const unsigned*)((const char*)(gbase) + (voff)[_i]), (PG8_LAS unsigned*)(lds + (bufoff) + ldsw + _i * 8192), 16, 0, 0); } while (0)
; #define PG8_LDA(dst, b, h) do { _Pragma("unroll") for (int m = 0; m < 4; ++m) _Pragma("unroll") for (int k = 0; k < 2; ++k) dst[m][k] = *(const PG8_LAS bf16x8*)(lds + PG8_SA(b, h) + aoff + m * 2048 + k * 1024); } while (0)
; #define PG8_LDB(dst, b, h) do { _Pragma("unroll") for (int n = 0; n < 2; ++n) _Pragma("unroll") for (int k = 0; k < 2; ++k) dst[n][k] = *(const PG8_LAS bf16x8*)(lds + PG8_SB(b, h) + boff + n * 2048 + k * 1024); } while (0)
; #define PG8_WAIT_V(n) asm volatile("s_waitcnt vmcnt(" #n ")" ::: "memory")
; #define PG8_WAIT_L(n) asm volatile("s_waitcnt lgkmcnt(" #n ")" ::: "memory")
; #define PG8_BAR __builtin_amdgcn_s_barrier()
; #define PG8_SCHED __builtin_amdgcn_sched_barrier(0)
; template <class Epi, class Sched, bool ALIGN_EPI = false, bool SP2 = false, bool F16 = false>
; __device__ __forceinline__ void gemm_phase(PG8_LAS unsigned char* lds, const Gemm g, const Sched& S, const Epi& E) {
;     ...
;             PG8_LDB(B0, 1, 0); PG8_LDB(B1, 1, 1); PG8_SCHED; PG8_LDA(At, 1, 0); PG8_STAGE(PG8_SA(0, 1), a2 + hstepA, voffA);
;             PG8_WAIT_V(8); PG8_WAIT_L(0); PG8_BAR; PG8_MMA(0, 0, At, B0); PG8_MMA(0, 1, At, B1); PG8_BAR; PG8_SCHED;
;             PG8_LDA(At, 1, 1); PG8_STAGE(PG8_SB(1, 0), b3, voffB); PG8_STAGE(PG8_SB(1, 1), b3 + hstepB, voffB); PG8_STAGE(PG8_SA(1, 0), a3, voffA);
;             PG8_WAIT_V(8); PG8_WAIT_L(0); PG8_BAR; PG8_MMA(1, 0, At, B0); PG8_MMA(1, 1, At, B1); PG8_BAR; PG8_SCHED;
	s_setprio 0
	s_add_i32 s79, 0, 0x18000
	s_add_i32 s94, 0, 0x1c000
	ds_read_b128 v[130:133], v159
	ds_read_b128 v[134:137], v159 offset:1024
	ds_read_b128 v[138:141], v159 offset:2048
	ds_read_b128 v[142:145], v159 offset:3072
	ds_read_b128 v[146:149], v161
	ds_read_b128 v[150:153], v161 offset:1024
	ds_read_b128 v[182:185], v161 offset:2048
	ds_read_b128 v[186:189], v161 offset:3072
	s_add_u32 s72, s72, s8
	s_addc_u32 s73, s73, 0
	s_mov_b32 m0, s35
	ds_read_b128 v[190:193], v204 offset:32768
	ds_read_b128 v[194:197], v204 offset:33792
	ds_read_b128 v[206:209], v204 offset:34816
	ds_read_b128 v[210:213], v204 offset:35840
	ds_read_b128 v[214:217], v204 offset:36864
	ds_read_b128 v[218:221], v204 offset:37888
	ds_read_b128 v[222:225], v204 offset:38912
	ds_read_b128 v[226:229], v204 offset:39936
	global_load_lds_dwordx4 v154, s[72:73]
	s_mov_b32 m0, s2
	s_nop 0
	global_load_lds_dwordx4 v158, s[72:73]
	s_waitcnt vmcnt(8)
	s_waitcnt lgkmcnt(0)
	s_setprio 1
	s_barrier
	v_mfma_f32_16x16x32_bf16 v[122:125], v[130:133], v[190:193], v[122:125]
	v_mfma_f32_16x16x32_bf16 v[126:129], v[138:141], v[190:193], v[126:129]
	v_mfma_f32_16x16x32_bf16 v[110:113], v[130:133], v[206:209], v[110:113]
	v_mfma_f32_16x16x32_bf16 v[106:109], v[138:141], v[206:209], v[106:109]
	v_mfma_f32_16x16x32_bf16 v[94:97], v[130:133], v[214:217], v[94:97]
	v_mfma_f32_16x16x32_bf16 v[90:93], v[138:141], v[214:217], v[90:93]
	v_mfma_f32_16x16x32_bf16 v[78:81], v[130:133], v[222:225], v[78:81]
	v_mfma_f32_16x16x32_bf16 v[74:77], v[138:141], v[222:225], v[74:77]
	v_mfma_f32_16x16x32_bf16 v[122:125], v[134:137], v[194:197], v[122:125]
	v_mfma_f32_16x16x32_bf16 v[126:129], v[142:145], v[194:197], v[126:129]
	v_mfma_f32_16x16x32_bf16 v[110:113], v[134:137], v[210:213], v[110:113]
	v_mfma_f32_16x16x32_bf16 v[106:109], v[142:145], v[210:213], v[106:109]
	v_mfma_f32_16x16x32_bf16 v[94:97], v[134:137], v[218:221], v[94:97]
	v_mfma_f32_16x16x32_bf16 v[90:93], v[142:145], v[218:221], v[90:93]
	v_mfma_f32_16x16x32_bf16 v[78:81], v[134:137], v[226:229], v[78:81]
	v_mfma_f32_16x16x32_bf16 v[74:77], v[142:145], v[226:229], v[74:77]
	v_mfma_f32_16x16x32_bf16 v[118:121], v[146:149], v[190:193], v[118:121]
	v_mfma_f32_16x16x32_bf16 v[114:117], v[182:185], v[190:193], v[114:117]
	v_mfma_f32_16x16x32_bf16 v[102:105], v[146:149], v[206:209], v[102:105]
	v_mfma_f32_16x16x32_bf16 v[98:101], v[182:185], v[206:209], v[98:101]
	v_mfma_f32_16x16x32_bf16 v[86:89], v[146:149], v[214:217], v[86:89]
	v_mfma_f32_16x16x32_bf16 v[82:85], v[182:185], v[214:217], v[82:85]
	v_mfma_f32_16x16x32_bf16 v[70:73], v[146:149], v[222:225], v[70:73]
	v_mfma_f32_16x16x32_bf16 v[66:69], v[182:185], v[222:225], v[66:69]
	v_mfma_f32_16x16x32_bf16 v[118:121], v[150:153], v[194:197], v[118:121]
	v_mfma_f32_16x16x32_bf16 v[114:117], v[186:189], v[194:197], v[114:117]
	v_mfma_f32_16x16x32_bf16 v[102:105], v[150:153], v[210:213], v[102:105]
	v_mfma_f32_16x16x32_bf16 v[98:101], v[186:189], v[210:213], v[98:101]
	v_mfma_f32_16x16x32_bf16 v[86:89], v[150:153], v[218:221], v[86:89]
	v_mfma_f32_16x16x32_bf16 v[82:85], v[186:189], v[218:221], v[82:85]
	v_mfma_f32_16x16x32_bf16 v[70:73], v[150:153], v[226:229], v[70:73]
	v_mfma_f32_16x16x32_bf16 v[66:69], v[186:189], v[226:229], v[66:69]
	s_barrier
	s_setprio 0
	s_add_i32 s72, s79, s75
	s_add_i32 vcc_hi, s78, -2
	s_cmp_eq_u32 s74, vcc_hi
	s_cselect_b32 s99, s53, s24
	s_cselect_b32 s98, s52, s13
	s_add_u32 s98, s98, s92
	s_addc_u32 s99, s99, s93
	s_mov_b32 m0, s72
	s_nop 0
	global_load_lds_dwordx4 v156, s[98:99]
	ds_read_b128 v[190:193], v204 offset:49152
	ds_read_b128 v[194:197], v204 offset:50176
	ds_read_b128 v[206:209], v204 offset:51200
	ds_read_b128 v[210:213], v204 offset:52224
	ds_read_b128 v[214:217], v204 offset:53248
	ds_read_b128 v[218:221], v204 offset:54272
	ds_read_b128 v[222:225], v204 offset:55296
	ds_read_b128 v[226:229], v204 offset:56320
	s_add_i32 m0, s72, 0x2000
	s_nop 0
	global_load_lds_dwordx4 v160, s[98:99]
	s_add_i32 s72, s94, s75
	s_add_u32 s98, s98, s48
	s_addc_u32 s99, s99, 0
	s_mov_b32 m0, s72
	s_nop 0
	global_load_lds_dwordx4 v156, s[98:99]
	s_add_i32 m0, s72, 0x2000
	s_nop 0
	global_load_lds_dwordx4 v160, s[98:99]
	s_add_u32 s98, s46, 0x80
	s_addc_u32 s99, s47, 0
	s_cmp_eq_u32 s74, vcc_hi
	s_cselect_b32 s99, s55, s99
	s_cselect_b32 s98, s54, s98
	s_add_u32 s98, s98, s92
	s_addc_u32 s99, s99, s93
	s_mov_b32 m0, s22
	s_nop 0
	global_load_lds_dwordx4 v154, s[98:99]
	s_mov_b32 m0, s23
	s_nop 0
	global_load_lds_dwordx4 v158, s[98:99]
	s_waitcnt vmcnt(8)
	s_waitcnt lgkmcnt(0)
	s_setprio 1
	s_barrier
	v_mfma_f32_16x16x32_bf16 v[62:65], v[130:133], v[190:193], v[62:65]
	v_mfma_f32_16x16x32_bf16 v[58:61], v[138:141], v[190:193], v[58:61]
	v_mfma_f32_16x16x32_bf16 v[46:49], v[130:133], v[206:209], v[46:49]
	v_mfma_f32_16x16x32_bf16 v[42:45], v[138:141], v[206:209], v[42:45]
	v_mfma_f32_16x16x32_bf16 v[30:33], v[130:133], v[214:217], v[30:33]
	v_mfma_f32_16x16x32_bf16 v[26:29], v[138:141], v[214:217], v[26:29]
	v_mfma_f32_16x16x32_bf16 v[14:17], v[130:133], v[222:225], v[14:17]
	v_mfma_f32_16x16x32_bf16 v[10:13], v[138:141], v[222:225], v[10:13]
	v_mfma_f32_16x16x32_bf16 v[62:65], v[134:137], v[194:197], v[62:65]
	v_mfma_f32_16x16x32_bf16 v[58:61], v[142:145], v[194:197], v[58:61]
	v_mfma_f32_16x16x32_bf16 v[46:49], v[134:137], v[210:213], v[46:49]
	v_mfma_f32_16x16x32_bf16 v[42:45], v[142:145], v[210:213], v[42:45]
	v_mfma_f32_16x16x32_bf16 v[30:33], v[134:137], v[218:221], v[30:33]
	v_mfma_f32_16x16x32_bf16 v[26:29], v[142:145], v[218:221], v[26:29]
	v_mfma_f32_16x16x32_bf16 v[14:17], v[134:137], v[226:229], v[14:17]
	v_mfma_f32_16x16x32_bf16 v[10:13], v[142:145], v[226:229], v[10:13]
	v_mfma_f32_16x16x32_bf16 v[54:57], v[146:149], v[190:193], v[54:57]
	v_mfma_f32_16x16x32_bf16 v[50:53], v[182:185], v[190:193], v[50:53]
	v_mfma_f32_16x16x32_bf16 v[38:41], v[146:149], v[206:209], v[38:41]
	v_mfma_f32_16x16x32_bf16 v[34:37], v[182:185], v[206:209], v[34:37]
	v_mfma_f32_16x16x32_bf16 v[22:25], v[146:149], v[214:217], v[22:25]
	v_mfma_f32_16x16x32_bf16 v[18:21], v[182:185], v[214:217], v[18:21]
	v_mfma_f32_16x16x32_bf16 v[6:9], v[146:149], v[222:225], v[6:9]
	v_mfma_f32_16x16x32_bf16 v[2:5], v[182:185], v[222:225], v[2:5]
	v_mfma_f32_16x16x32_bf16 v[54:57], v[150:153], v[194:197], v[54:57]
	v_mfma_f32_16x16x32_bf16 v[50:53], v[186:189], v[194:197], v[50:53]
	v_mfma_f32_16x16x32_bf16 v[38:41], v[150:153], v[210:213], v[38:41]
	v_mfma_f32_16x16x32_bf16 v[34:37], v[186:189], v[210:213], v[34:37]
	v_mfma_f32_16x16x32_bf16 v[22:25], v[150:153], v[218:221], v[22:25]
	v_mfma_f32_16x16x32_bf16 v[18:21], v[186:189], v[218:221], v[18:21]
	v_mfma_f32_16x16x32_bf16 v[6:9], v[150:153], v[226:229], v[6:9]
	v_mfma_f32_16x16x32_bf16 v[2:5], v[186:189], v[226:229], v[2:5]
	s_barrier
	s_setprio 0
	s_add_u32 s46, s46, 0x100
	s_addc_u32 s47, s47, 0
	s_add_u32 s13, s13, 0x100
	s_addc_u32 s24, s24, 0
	s_cmp_ge_u32 s78, s65
	s_mov_b32 s72, s78
	s_cbranch_scc1 .LBB0_399

; #define PG8_BAR __builtin_amdgcn_s_barrier()
; template <class Epi, class Sched, bool ALIGN_EPI = false, bool SP2 = false, bool F16 = false>
; __device__ __forceinline__ void gemm_phase(PG8_LAS unsigned char* lds, const Gemm g, const Sched& S, const Epi& E) {
;     ...
;         if constexpr (ALIGN_EPI) { if (wr == 0) PG8_BAR; }
;         if constexpr (!Epi::AFTER_DRAIN) { E(acc, cur, wr, wc, fr, fq); S.done(cur); }
.LBB0_401:
	s_cmp_lg_u64 s[80:81], 0
	s_cbranch_scc0 .Lep_bf
	s_setprio 1

; #define PG8_WAIT_V(n) asm volatile("s_waitcnt vmcnt(" #n ")" ::: "memory")
; #define PG8_BAR __builtin_amdgcn_s_barrier()
; template <class Epi, class Sched, bool ALIGN_EPI = false, bool SP2 = false, bool F16 = false>
; __device__ __forceinline__ void gemm_phase(PG8_LAS unsigned char* lds, const Gemm g, const Sched& S, const Epi& E) {
;     ...
;     PG8_WAIT_V(0);
;     if constexpr (!ALIGN_EPI) { if (wr == 0) PG8_BAR; }
;     PG8_BAR;
.LBB0_538:
	s_setprio 0
	s_waitcnt vmcnt(0)
	v_readlane_b32 s72, v249, 34
	v_readlane_b32 s54, v249, 38
	v_readlane_b32 s40, v248, 29
	s_barrier
	v_readlane_b32 s73, v249, 35
	v_readlane_b32 s55, v249, 39
	v_readlane_b32 s35, v249, 40
	v_readlane_b32 s75, v249, 41
	v_readlane_b32 s78, v249, 42
	s_movk_i32 s59, 0x6000
	v_readlane_b32 s41, v248, 30

; #define PG8_STAGE(bufoff, gbase, voff) do { _Pragma("unroll") for (int _i = 0; _i < 2; ++_i) \
;         __builtin_amdgcn_global_load_lds((const unsigned*)((const char*)(gbase) + (voff)[_i]), (PG8_LAS unsigned*)(lds + (bufoff) + ldsw + _i * 8192), 16, 0, 0); } while (0)
; #define PG8_LDA(dst, b, h) do { _Pragma("unroll") for (int m = 0; m < 4; ++m) _Pragma("unroll") for (int k = 0; k < 2; ++k) dst[m][k] = *(const PG8_LAS bf16x8*)(lds + PG8_SA(b, h) + aoff + m * 2048 + k * 1024); } while (0)
; #define PG8_LDB(dst, b, h) do { _Pragma("unroll") for (int n = 0; n < 2; ++n) _Pragma("unroll") for (int k = 0; k < 2; ++k) dst[n][k] = *(const PG8_LAS bf16x8*)(lds + PG8_SB(b, h) + boff + n * 2048 + k * 1024); } while (0)
; #define PG8_WAIT_V(n) asm volatile("s_waitcnt vmcnt(" #n ")" ::: "memory")
; #define PG8_WAIT_L(n) asm volatile("s_waitcnt lgkmcnt(" #n ")" ::: "memory")
; #define PG8_BAR __builtin_amdgcn_s_barrier()
; #define PG8_SCHED __builtin_amdgcn_sched_barrier(0)
; template <class Epi, class Sched, bool ALIGN_EPI = false, bool SP2 = false, bool F16 = false>
; __device__ __forceinline__ void gemm_phase(PG8_LAS unsigned char* lds, const Gemm g, const Sched& S, const Epi& E) {
;     ...
;             if constexpr (SP2) {
;             PG8_LDB(B0, 0, 0); PG8_LDB(B1, 0, 1); PG8_SCHED; PG8_LDA(At, 0, 0); PG8_STAGE(PG8_SA(1, 1), a1 + hstepA, voffA);
;             PG8_WAIT_V(8); PG8_WAIT_L(0); PG8_BAR; PG8_MMA(0, 0, At, B0); PG8_MMA(0, 1, At, B1); PG8_BAR; PG8_SCHED;
;             PG8_LDA(At, 0, 1); PG8_STAGE(PG8_SB(0, 0), b2, voffB); PG8_STAGE(PG8_SB(0, 1), b2 + hstepB, voffB); PG8_STAGE(PG8_SA(0, 0), a2, voffA);
;             PG8_WAIT_V(8); PG8_WAIT_L(0); PG8_BAR; PG8_MMA(1, 0, At, B0); PG8_MMA(1, 1, At, B1); PG8_BAR; PG8_SCHED;
.Lpk_bh:
	s_setprio 0
	s_add_i32 s73, s52, 2
	s_add_u32 s82, s44, 0x80
	s_addc_u32 s53, s45, 0
	s_add_i32 s94, 0, 0x10000
	s_cmp_eq_u32 s74, s52
	s_cselect_b32 s53, s79, s53
	s_cselect_b32 s52, s78, s82
	s_cselect_b32 s83, s55, s72
	s_cselect_b32 s82, s54, s24
	s_add_i32 s95, 0, 0x14000
	ds_read_b128 v[130:133], v155
	ds_read_b128 v[134:137], v155 offset:1024
	ds_read_b128 v[138:141], v155 offset:2048
	ds_read_b128 v[142:145], v155 offset:3072
	ds_read_b128 v[146:149], v157
	ds_read_b128 v[150:153], v157 offset:1024
	ds_read_b128 v[182:185], v157 offset:2048
	ds_read_b128 v[186:189], v157 offset:3072
	s_add_i32 m0, s35, 0xc000
	ds_read_b128 v[190:193], v204
	ds_read_b128 v[194:197], v204 offset:1024
	ds_read_b128 v[206:209], v204 offset:2048
	ds_read_b128 v[210:213], v204 offset:3072
	ds_read_b128 v[214:217], v204 offset:4096
	ds_read_b128 v[218:221], v204 offset:5120
	ds_read_b128 v[222:225], v204 offset:6144
	ds_read_b128 v[226:229], v204 offset:7168
	global_load_lds_dwordx4 v168, s[44:45]
	s_add_i32 m0, s35, 0xe000
	s_nop 0
	global_load_lds_dwordx4 v170, s[44:45]
	s_waitcnt vmcnt(8)
	s_waitcnt lgkmcnt(0)
	s_setprio 1
	s_barrier
	v_mfma_f32_16x16x32_f16 v[122:125], v[130:133], v[190:193], 0
	v_mfma_f32_16x16x32_f16 v[126:129], v[138:141], v[190:193], 0
	v_mfma_f32_16x16x32_f16 v[110:113], v[130:133], v[206:209], 0
	v_mfma_f32_16x16x32_f16 v[106:109], v[138:141], v[206:209], 0
	v_mfma_f32_16x16x32_f16 v[94:97], v[130:133], v[214:217], 0
	v_mfma_f32_16x16x32_f16 v[90:93], v[138:141], v[214:217], 0
	v_mfma_f32_16x16x32_f16 v[78:81], v[130:133], v[222:225], 0
	v_mfma_f32_16x16x32_f16 v[74:77], v[138:141], v[222:225], 0
	v_mfma_f32_16x16x32_f16 v[122:125], v[134:137], v[194:197], v[122:125]
	v_mfma_f32_16x16x32_f16 v[126:129], v[142:145], v[194:197], v[126:129]
	v_mfma_f32_16x16x32_f16 v[110:113], v[134:137], v[210:213], v[110:113]
	v_mfma_f32_16x16x32_f16 v[106:109], v[142:145], v[210:213], v[106:109]
	v_mfma_f32_16x16x32_f16 v[94:97], v[134:137], v[218:221], v[94:97]
	v_mfma_f32_16x16x32_f16 v[90:93], v[142:145], v[218:221], v[90:93]
	v_mfma_f32_16x16x32_f16 v[78:81], v[134:137], v[226:229], v[78:81]
	v_mfma_f32_16x16x32_f16 v[74:77], v[142:145], v[226:229], v[74:77]
	v_mfma_f32_16x16x32_f16 v[118:121], v[146:149], v[190:193], 0
	v_mfma_f32_16x16x32_f16 v[114:117], v[182:185], v[190:193], 0
	v_mfma_f32_16x16x32_f16 v[102:105], v[146:149], v[206:209], 0
	v_mfma_f32_16x16x32_f16 v[98:101], v[182:185], v[206:209], 0
	v_mfma_f32_16x16x32_f16 v[86:89], v[146:149], v[214:217], 0
	v_mfma_f32_16x16x32_f16 v[82:85], v[182:185], v[214:217], 0
	v_mfma_f32_16x16x32_f16 v[70:73], v[146:149], v[222:225], 0
	v_mfma_f32_16x16x32_f16 v[66:69], v[182:185], v[222:225], 0
	v_mfma_f32_16x16x32_f16 v[118:121], v[150:153], v[194:197], v[118:121]
	v_mfma_f32_16x16x32_f16 v[114:117], v[186:189], v[194:197], v[114:117]
	v_mfma_f32_16x16x32_f16 v[102:105], v[150:153], v[210:213], v[102:105]
	v_mfma_f32_16x16x32_f16 v[98:101], v[186:189], v[210:213], v[98:101]
	v_mfma_f32_16x16x32_f16 v[86:89], v[150:153], v[218:221], v[86:89]
	v_mfma_f32_16x16x32_f16 v[82:85], v[186:189], v[218:221], v[82:85]
	v_mfma_f32_16x16x32_f16 v[70:73], v[150:153], v[226:229], v[70:73]
	v_mfma_f32_16x16x32_f16 v[66:69], v[186:189], v[226:229], v[66:69]
	s_barrier
	s_setprio 0
	s_add_i32 s94, s94, s75
	s_mov_b32 m0, s94
	s_nop 0
	global_load_lds_dwordx4 v156, s[82:83]
	ds_read_b128 v[190:193], v204 offset:16384
	ds_read_b128 v[194:197], v204 offset:17408
	ds_read_b128 v[206:209], v204 offset:18432
	ds_read_b128 v[210:213], v204 offset:19456
	ds_read_b128 v[214:217], v204 offset:20480
	ds_read_b128 v[218:221], v204 offset:21504
	ds_read_b128 v[222:225], v204 offset:22528
	ds_read_b128 v[226:229], v204 offset:23552
	s_add_i32 m0, s94, 0x2000
	s_nop 0
	global_load_lds_dwordx4 v160, s[82:83]
	s_add_i32 s94, s95, s75
	s_add_u32 s82, s82, s48
	s_addc_u32 s83, s83, 0
	s_mov_b32 m0, s94
	s_nop 0
	global_load_lds_dwordx4 v156, s[82:83]
	s_add_i32 m0, s94, 0x2000
	s_nop 0
	global_load_lds_dwordx4 v160, s[82:83]
	s_mov_b32 m0, s35
	s_nop 0
	global_load_lds_dwordx4 v154, s[52:53]
	s_mov_b32 m0, s2
	s_nop 0
	global_load_lds_dwordx4 v158, s[52:53]
	s_waitcnt vmcnt(8)
	s_waitcnt lgkmcnt(0)
	s_setprio 1
	s_barrier
	v_mfma_f32_16x16x32_f16 v[62:65], v[130:133], v[190:193], 0
	v_mfma_f32_16x16x32_f16 v[58:61], v[138:141], v[190:193], 0
	v_mfma_f32_16x16x32_f16 v[46:49], v[130:133], v[206:209], 0
	v_mfma_f32_16x16x32_f16 v[42:45], v[138:141], v[206:209], 0
	v_mfma_f32_16x16x32_f16 v[30:33], v[130:133], v[214:217], 0
	v_mfma_f32_16x16x32_f16 v[26:29], v[138:141], v[214:217], 0
	v_mfma_f32_16x16x32_f16 v[14:17], v[130:133], v[222:225], 0
	v_mfma_f32_16x16x32_f16 v[10:13], v[138:141], v[222:225], 0
	v_mfma_f32_16x16x32_f16 v[62:65], v[134:137], v[194:197], v[62:65]
	v_mfma_f32_16x16x32_f16 v[58:61], v[142:145], v[194:197], v[58:61]
	v_mfma_f32_16x16x32_f16 v[46:49], v[134:137], v[210:213], v[46:49]
	v_mfma_f32_16x16x32_f16 v[42:45], v[142:145], v[210:213], v[42:45]
	v_mfma_f32_16x16x32_f16 v[30:33], v[134:137], v[218:221], v[30:33]
	v_mfma_f32_16x16x32_f16 v[26:29], v[142:145], v[218:221], v[26:29]
	v_mfma_f32_16x16x32_f16 v[14:17], v[134:137], v[226:229], v[14:17]
	v_mfma_f32_16x16x32_f16 v[10:13], v[142:145], v[226:229], v[10:13]
	v_mfma_f32_16x16x32_f16 v[54:57], v[146:149], v[190:193], 0
	v_mfma_f32_16x16x32_f16 v[50:53], v[182:185], v[190:193], 0
	v_mfma_f32_16x16x32_f16 v[38:41], v[146:149], v[206:209], 0
	v_mfma_f32_16x16x32_f16 v[34:37], v[182:185], v[206:209], 0
	v_mfma_f32_16x16x32_f16 v[22:25], v[146:149], v[214:217], 0
	v_mfma_f32_16x16x32_f16 v[18:21], v[182:185], v[214:217], 0
	v_mfma_f32_16x16x32_f16 v[6:9], v[146:149], v[222:225], 0
	v_mfma_f32_16x16x32_f16 v[2:5], v[182:185], v[222:225], 0
	v_mfma_f32_16x16x32_f16 v[54:57], v[150:153], v[194:197], v[54:57]
	v_mfma_f32_16x16x32_f16 v[50:53], v[186:189], v[194:197], v[50:53]
	v_mfma_f32_16x16x32_f16 v[38:41], v[150:153], v[210:213], v[38:41]
	v_mfma_f32_16x16x32_f16 v[34:37], v[186:189], v[210:213], v[34:37]
	v_mfma_f32_16x16x32_f16 v[22:25], v[150:153], v[218:221], v[22:25]
	v_mfma_f32_16x16x32_f16 v[18:21], v[186:189], v[218:221], v[18:21]
	v_mfma_f32_16x16x32_f16 v[6:9], v[150:153], v[226:229], v[6:9]
	v_mfma_f32_16x16x32_f16 v[2:5], v[186:189], v[226:229], v[2:5]
	s_barrier
; #define PG8_STAGE(bufoff, gbase, voff) do { _Pragma("unroll") for (int _i = 0; _i < 2; ++_i) \
;         __builtin_amdgcn_global_load_lds((const unsigned*)((const char*)(gbase) + (voff)[_i]), (PG8_LAS unsigned*)(lds + (bufoff) + ldsw + _i * 8192), 16, 0, 0); } while (0)
; #define PG8_LDA(dst, b, h) do { _Pragma("unroll") for (int m = 0; m < 4; ++m) _Pragma("unroll") for (int k = 0; k < 2; ++k) dst[m][k] = *(const PG8_LAS bf16x8*)(lds + PG8_SA(b, h) + aoff + m * 2048 + k * 1024); } while (0)
; #define PG8_LDB(dst, b, h) do { _Pragma("unroll") for (int n = 0; n < 2; ++n) _Pragma("unroll") for (int k = 0; k < 2; ++k) dst[n][k] = *(const PG8_LAS bf16x8*)(lds + PG8_SB(b, h) + boff + n * 2048 + k * 1024); } while (0)
; #define PG8_WAIT_V(n) asm volatile("s_waitcnt vmcnt(" #n ")" ::: "memory")
; #define PG8_WAIT_L(n) asm volatile("s_waitcnt lgkmcnt(" #n ")" ::: "memory")
; #define PG8_BAR __builtin_amdgcn_s_barrier()
; #define PG8_SCHED __builtin_amdgcn_sched_barrier(0)
; template <class Epi, class Sched, bool ALIGN_EPI = false, bool SP2 = false, bool F16 = false>
; __device__ __forceinline__ void gemm_phase(PG8_LAS unsigned char* lds, const Gemm g, const Sched& S, const Epi& E) {
;     ...
;             PG8_LDB(B0, 1, 0); PG8_LDB(B1, 1, 1); PG8_SCHED; PG8_LDA(At, 1, 0); PG8_STAGE(PG8_SA(0, 1), a2 + hstepA, voffA);
;             PG8_WAIT_V(8); PG8_WAIT_L(0); PG8_BAR; PG8_MMA(0, 0, At, B0); PG8_MMA(0, 1, At, B1); PG8_BAR; PG8_SCHED;
;             PG8_LDA(At, 1, 1); PG8_STAGE(PG8_SB(1, 0), b3, voffB); PG8_STAGE(PG8_SB(1, 1), b3 + hstepB, voffB); PG8_STAGE(PG8_SA(1, 0), a3, voffA);
;             PG8_WAIT_V(8); PG8_WAIT_L(0); PG8_BAR; PG8_MMA(1, 0, At, B0); PG8_MMA(1, 1, At, B1); PG8_BAR; PG8_SCHED;
	s_setprio 0
	s_add_i32 s82, 0, 0x18000
	s_add_i32 s83, 0, 0x1c000
	ds_read_b128 v[130:133], v159
	ds_read_b128 v[134:137], v159 offset:1024
	ds_read_b128 v[138:141], v159 offset:2048
	ds_read_b128 v[142:145], v159 offset:3072
	ds_read_b128 v[146:149], v161
	ds_read_b128 v[150:153], v161 offset:1024
	ds_read_b128 v[182:185], v161 offset:2048
	ds_read_b128 v[186:189], v161 offset:3072
	s_add_u32 s52, s52, s8
	s_addc_u32 s53, s53, 0
	s_mov_b32 m0, s22
	ds_read_b128 v[190:193], v204 offset:32768
	ds_read_b128 v[194:197], v204 offset:33792
	ds_read_b128 v[206:209], v204 offset:34816
	ds_read_b128 v[210:213], v204 offset:35840
	ds_read_b128 v[214:217], v204 offset:36864
	ds_read_b128 v[218:221], v204 offset:37888
	ds_read_b128 v[222:225], v204 offset:38912
	ds_read_b128 v[226:229], v204 offset:39936
	global_load_lds_dwordx4 v154, s[52:53]
	s_mov_b32 m0, s23
	s_nop 0
	global_load_lds_dwordx4 v158, s[52:53]
	s_waitcnt vmcnt(8)
	s_waitcnt lgkmcnt(0)
	s_setprio 1
	s_barrier
	v_mfma_f32_16x16x32_f16 v[122:125], v[130:133], v[190:193], v[122:125]
	v_mfma_f32_16x16x32_f16 v[126:129], v[138:141], v[190:193], v[126:129]
	v_mfma_f32_16x16x32_f16 v[110:113], v[130:133], v[206:209], v[110:113]
	v_mfma_f32_16x16x32_f16 v[106:109], v[138:141], v[206:209], v[106:109]
	v_mfma_f32_16x16x32_f16 v[94:97], v[130:133], v[214:217], v[94:97]
	v_mfma_f32_16x16x32_f16 v[90:93], v[138:141], v[214:217], v[90:93]
	v_mfma_f32_16x16x32_f16 v[78:81], v[130:133], v[222:225], v[78:81]
	v_mfma_f32_16x16x32_f16 v[74:77], v[138:141], v[222:225], v[74:77]
	v_mfma_f32_16x16x32_f16 v[122:125], v[134:137], v[194:197], v[122:125]
	v_mfma_f32_16x16x32_f16 v[126:129], v[142:145], v[194:197], v[126:129]
	v_mfma_f32_16x16x32_f16 v[110:113], v[134:137], v[210:213], v[110:113]
	v_mfma_f32_16x16x32_f16 v[106:109], v[142:145], v[210:213], v[106:109]
	v_mfma_f32_16x16x32_f16 v[94:97], v[134:137], v[218:221], v[94:97]
	v_mfma_f32_16x16x32_f16 v[90:93], v[142:145], v[218:221], v[90:93]
	v_mfma_f32_16x16x32_f16 v[78:81], v[134:137], v[226:229], v[78:81]
	v_mfma_f32_16x16x32_f16 v[74:77], v[142:145], v[226:229], v[74:77]
	v_mfma_f32_16x16x32_f16 v[118:121], v[146:149], v[190:193], v[118:121]
	v_mfma_f32_16x16x32_f16 v[114:117], v[182:185], v[190:193], v[114:117]
	v_mfma_f32_16x16x32_f16 v[102:105], v[146:149], v[206:209], v[102:105]
	v_mfma_f32_16x16x32_f16 v[98:101], v[182:185], v[206:209], v[98:101]
	v_mfma_f32_16x16x32_f16 v[86:89], v[146:149], v[214:217], v[86:89]
	v_mfma_f32_16x16x32_f16 v[82:85], v[182:185], v[214:217], v[82:85]
	v_mfma_f32_16x16x32_f16 v[70:73], v[146:149], v[222:225], v[70:73]
	v_mfma_f32_16x16x32_f16 v[66:69], v[182:185], v[222:225], v[66:69]
	v_mfma_f32_16x16x32_f16 v[118:121], v[150:153], v[194:197], v[118:121]
	v_mfma_f32_16x16x32_f16 v[114:117], v[186:189], v[194:197], v[114:117]
	v_mfma_f32_16x16x32_f16 v[102:105], v[150:153], v[210:213], v[102:105]
	v_mfma_f32_16x16x32_f16 v[98:101], v[186:189], v[210:213], v[98:101]
	v_mfma_f32_16x16x32_f16 v[86:89], v[150:153], v[218:221], v[86:89]
	v_mfma_f32_16x16x32_f16 v[82:85], v[186:189], v[218:221], v[82:85]
	v_mfma_f32_16x16x32_f16 v[70:73], v[150:153], v[226:229], v[70:73]
	v_mfma_f32_16x16x32_f16 v[66:69], v[186:189], v[226:229], v[66:69]
	s_barrier
	s_setprio 0
	s_add_i32 s52, s82, s75
	s_add_i32 vcc_hi, s73, -2
	s_cmp_eq_u32 s74, vcc_hi
	s_cselect_b32 s99, s55, s72
	s_cselect_b32 s98, s54, s24
	s_add_u32 s98, s98, s92
	s_addc_u32 s99, s99, s93
	s_mov_b32 m0, s52
	s_nop 0
	global_load_lds_dwordx4 v156, s[98:99]
	ds_read_b128 v[190:193], v204 offset:49152
	ds_read_b128 v[194:197], v204 offset:50176
	ds_read_b128 v[206:209], v204 offset:51200
	ds_read_b128 v[210:213], v204 offset:52224
	ds_read_b128 v[214:217], v204 offset:53248
	ds_read_b128 v[218:221], v204 offset:54272
	ds_read_b128 v[222:225], v204 offset:55296
	ds_read_b128 v[226:229], v204 offset:56320
	s_add_i32 m0, s52, 0x2000
	s_nop 0
	global_load_lds_dwordx4 v160, s[98:99]
	s_add_i32 s52, s83, s75
	s_add_u32 s98, s98, s48
	s_addc_u32 s99, s99, 0
	s_mov_b32 m0, s52
	s_nop 0
	global_load_lds_dwordx4 v156, s[98:99]
	s_add_i32 m0, s52, 0x2000
	s_nop 0
	global_load_lds_dwordx4 v160, s[98:99]
	s_add_u32 s98, s44, 0x80
	s_addc_u32 s99, s45, 0
	s_cmp_eq_u32 s74, vcc_hi
	s_cselect_b32 s99, s79, s99
	s_cselect_b32 s98, s78, s98
	s_add_u32 s98, s98, s92
	s_addc_u32 s99, s99, s93
	s_mov_b32 m0, s61
	s_nop 0
	global_load_lds_dwordx4 v154, s[98:99]
	s_mov_b32 m0, s18
	s_nop 0
	global_load_lds_dwordx4 v158, s[98:99]
	s_waitcnt vmcnt(8)
	s_waitcnt lgkmcnt(0)
	s_setprio 1
	s_barrier
	v_mfma_f32_16x16x32_f16 v[62:65], v[130:133], v[190:193], v[62:65]
	v_mfma_f32_16x16x32_f16 v[58:61], v[138:141], v[190:193], v[58:61]
	v_mfma_f32_16x16x32_f16 v[46:49], v[130:133], v[206:209], v[46:49]
	v_mfma_f32_16x16x32_f16 v[42:45], v[138:141], v[206:209], v[42:45]
	v_mfma_f32_16x16x32_f16 v[30:33], v[130:133], v[214:217], v[30:33]
	v_mfma_f32_16x16x32_f16 v[26:29], v[138:141], v[214:217], v[26:29]
	v_mfma_f32_16x16x32_f16 v[14:17], v[130:133], v[222:225], v[14:17]
	v_mfma_f32_16x16x32_f16 v[10:13], v[138:141], v[222:225], v[10:13]
	v_mfma_f32_16x16x32_f16 v[62:65], v[134:137], v[194:197], v[62:65]
	v_mfma_f32_16x16x32_f16 v[58:61], v[142:145], v[194:197], v[58:61]
	v_mfma_f32_16x16x32_f16 v[46:49], v[134:137], v[210:213], v[46:49]
	v_mfma_f32_16x16x32_f16 v[42:45], v[142:145], v[210:213], v[42:45]
	v_mfma_f32_16x16x32_f16 v[30:33], v[134:137], v[218:221], v[30:33]
	v_mfma_f32_16x16x32_f16 v[26:29], v[142:145], v[218:221], v[26:29]
	v_mfma_f32_16x16x32_f16 v[14:17], v[134:137], v[226:229], v[14:17]
	v_mfma_f32_16x16x32_f16 v[10:13], v[142:145], v[226:229], v[10:13]
	v_mfma_f32_16x16x32_f16 v[54:57], v[146:149], v[190:193], v[54:57]
	v_mfma_f32_16x16x32_f16 v[50:53], v[182:185], v[190:193], v[50:53]
	v_mfma_f32_16x16x32_f16 v[38:41], v[146:149], v[206:209], v[38:41]
	v_mfma_f32_16x16x32_f16 v[34:37], v[182:185], v[206:209], v[34:37]
	v_mfma_f32_16x16x32_f16 v[22:25], v[146:149], v[214:217], v[22:25]
	v_mfma_f32_16x16x32_f16 v[18:21], v[182:185], v[214:217], v[18:21]
	v_mfma_f32_16x16x32_f16 v[6:9], v[146:149], v[222:225], v[6:9]
	v_mfma_f32_16x16x32_f16 v[2:5], v[182:185], v[222:225], v[2:5]
	v_mfma_f32_16x16x32_f16 v[54:57], v[150:153], v[194:197], v[54:57]
	v_mfma_f32_16x16x32_f16 v[50:53], v[186:189], v[194:197], v[50:53]
	v_mfma_f32_16x16x32_f16 v[38:41], v[150:153], v[210:213], v[38:41]
	v_mfma_f32_16x16x32_f16 v[34:37], v[186:189], v[210:213], v[34:37]
	v_mfma_f32_16x16x32_f16 v[22:25], v[150:153], v[218:221], v[22:25]
	v_mfma_f32_16x16x32_f16 v[18:21], v[186:189], v[218:221], v[18:21]
	v_mfma_f32_16x16x32_f16 v[6:9], v[150:153], v[226:229], v[6:9]
	v_mfma_f32_16x16x32_f16 v[2:5], v[186:189], v[226:229], v[2:5]
	s_barrier
	s_setprio 0
	s_add_u32 s44, s44, 0x100
	s_addc_u32 s45, s45, 0
	s_add_u32 s24, s24, 0x100
	s_addc_u32 s72, s72, 0
	s_cmp_ge_u32 s73, s65
	s_mov_b32 s52, s73
	s_cbranch_scc1 .LBB0_565

; #define PG8_BAR __builtin_amdgcn_s_barrier()
; template <class Epi, class Sched, bool ALIGN_EPI = false, bool SP2 = false, bool F16 = false>
; __device__ __forceinline__ void gemm_phase(PG8_LAS unsigned char* lds, const Gemm g, const Sched& S, const Epi& E) {
;     ...
;         if constexpr (ALIGN_EPI) { if (wr == 0) PG8_BAR; }
;         if constexpr (!Epi::AFTER_DRAIN) { E(acc, cur, wr, wc, fr, fq); S.done(cur); }
.LBB0_567:
	s_cmp_lg_u64 s[46:47], 0
	s_cbranch_scc0 .Lep_bh
	s_setprio 1

; #define PG8_WAIT_V(n) asm volatile("s_waitcnt vmcnt(" #n ")" ::: "memory")
; #define PG8_BAR __builtin_amdgcn_s_barrier()
; template <class Epi, class Sched, bool ALIGN_EPI = false, bool SP2 = false, bool F16 = false>
; __device__ __forceinline__ void gemm_phase(PG8_LAS unsigned char* lds, const Gemm g, const Sched& S, const Epi& E) {
;     ...
;     PG8_WAIT_V(0);
;     if constexpr (!ALIGN_EPI) { if (wr == 0) PG8_BAR; }
;     PG8_BAR;
.LBB0_704:
	s_setprio 0
	s_waitcnt vmcnt(0)
	v_readlane_b32 s72, v249, 34
	v_readlane_b32 s54, v249, 38
	s_barrier
	v_readlane_b32 s73, v249, 35
	v_readlane_b32 s55, v249, 39
	v_readlane_b32 s35, v249, 40
	v_readlane_b32 s75, v249, 41
	v_readlane_b32 s78, v249, 42
	s_movk_i32 s59, 0x6000
